# v43 + s_setprio 1 during GEMM memory segments, 0 during MFMA segments (reverse of baseline)
# speedup vs baseline: 1.0068x; 1.0068x over previous
.LBB0_142:
	s_add_u32 s18, s16, 0xfffc0080
	s_addc_u32 s19, s17, -1
	s_add_i32 s28, 0, 0x10000
	s_cmp_eq_u32 s88, 12
	s_cselect_b32 s53, s47, s19
	s_cselect_b32 s52, s78, s18
	v_add_u32_e32 v140, s28, v143
	s_cselect_b32 s19, s15, s85
	s_cselect_b32 s18, s79, s83
	s_add_i32 s29, 0, 0x14000
	ds_read_b128 v[146:149], v140
	ds_read_b128 v[150:153], v140 offset:1024
	ds_read_b128 v[154:157], v140 offset:2048
	ds_read_b128 v[158:161], v140 offset:3072
	v_add_u32_e32 v140, s29, v143
	ds_read_b128 v[162:165], v140
	ds_read_b128 v[166:169], v140 offset:1024
	ds_read_b128 v[174:177], v140 offset:2048
	ds_read_b128 v[178:181], v140 offset:3072
	v_lshl_add_u64 v[140:141], s[16:17], 0, v[136:137]
	s_add_i32 m0, s54, 0xc000
	ds_read_b128 v[182:185], v145
	ds_read_b128 v[186:189], v145 offset:1024
	ds_read_b128 v[190:193], v145 offset:2048
	ds_read_b128 v[194:197], v145 offset:3072
	ds_read_b128 v[198:201], v145 offset:4096
	ds_read_b128 v[202:205], v145 offset:5120
	ds_read_b128 v[236:239], v145 offset:6144
	ds_read_b128 v[240:243], v145 offset:7168
	global_load_lds_dwordx4 v[140:141], off
	v_lshl_add_u64 v[140:141], s[16:17], 0, v[138:139]
	s_add_i32 m0, s54, 0xe000
	s_nop 0
	global_load_lds_dwordx4 v[140:141], off
	s_waitcnt vmcnt(8)
	s_waitcnt lgkmcnt(0)
	s_barrier
	s_setprio 0
	s_waitcnt lgkmcnt(0)
	v_mfma_f32_16x16x32_bf16 v[126:129], v[146:149], v[182:185], v[126:129]
	v_mfma_f32_16x16x32_bf16 v[118:121], v[154:157], v[182:185], v[118:121]
	v_mfma_f32_16x16x32_bf16 v[110:113], v[146:149], v[190:193], v[110:113]
	v_mfma_f32_16x16x32_bf16 v[102:105], v[154:157], v[190:193], v[102:105]
	v_mfma_f32_16x16x32_bf16 v[94:97], v[146:149], v[198:201], v[94:97]
	v_mfma_f32_16x16x32_bf16 v[86:89], v[154:157], v[198:201], v[86:89]
	v_mfma_f32_16x16x32_bf16 v[78:81], v[146:149], v[236:239], v[78:81]
	v_mfma_f32_16x16x32_bf16 v[70:73], v[154:157], v[236:239], v[70:73]
	v_mfma_f32_16x16x32_bf16 v[126:129], v[150:153], v[186:189], v[126:129]
	v_mfma_f32_16x16x32_bf16 v[118:121], v[158:161], v[186:189], v[118:121]
	v_mfma_f32_16x16x32_bf16 v[110:113], v[150:153], v[194:197], v[110:113]
	v_mfma_f32_16x16x32_bf16 v[102:105], v[158:161], v[194:197], v[102:105]
	v_mfma_f32_16x16x32_bf16 v[94:97], v[150:153], v[202:205], v[94:97]
	v_mfma_f32_16x16x32_bf16 v[86:89], v[158:161], v[202:205], v[86:89]
	v_mfma_f32_16x16x32_bf16 v[78:81], v[150:153], v[240:243], v[78:81]
	v_mfma_f32_16x16x32_bf16 v[70:73], v[158:161], v[240:243], v[70:73]
	v_mfma_f32_16x16x32_bf16 v[122:125], v[162:165], v[182:185], v[122:125]
	v_mfma_f32_16x16x32_bf16 v[114:117], v[174:177], v[182:185], v[114:117]
	v_mfma_f32_16x16x32_bf16 v[106:109], v[162:165], v[190:193], v[106:109]
	v_mfma_f32_16x16x32_bf16 v[98:101], v[174:177], v[190:193], v[98:101]
	v_mfma_f32_16x16x32_bf16 v[90:93], v[162:165], v[198:201], v[90:93]
	v_mfma_f32_16x16x32_bf16 v[82:85], v[174:177], v[198:201], v[82:85]
	v_mfma_f32_16x16x32_bf16 v[74:77], v[162:165], v[236:239], v[74:77]
	v_mfma_f32_16x16x32_bf16 v[66:69], v[174:177], v[236:239], v[66:69]
	v_mfma_f32_16x16x32_bf16 v[122:125], v[166:169], v[186:189], v[122:125]
	v_mfma_f32_16x16x32_bf16 v[114:117], v[178:181], v[186:189], v[114:117]
	v_mfma_f32_16x16x32_bf16 v[106:109], v[166:169], v[194:197], v[106:109]
	v_mfma_f32_16x16x32_bf16 v[98:101], v[178:181], v[194:197], v[98:101]
	v_mfma_f32_16x16x32_bf16 v[90:93], v[166:169], v[202:205], v[90:93]
	v_mfma_f32_16x16x32_bf16 v[82:85], v[178:181], v[202:205], v[82:85]
	v_mfma_f32_16x16x32_bf16 v[74:77], v[166:169], v[240:243], v[74:77]
	v_mfma_f32_16x16x32_bf16 v[66:69], v[178:181], v[240:243], v[66:69]
	s_barrier
	s_setprio 1
	s_add_i32 s28, s28, s41
	v_lshl_add_u64 v[140:141], s[18:19], 0, v[0:1]
	s_mov_b32 m0, s28
	ds_read_b128 v[182:185], v145 offset:16384
	ds_read_b128 v[186:189], v145 offset:17408
	ds_read_b128 v[190:193], v145 offset:18432
	ds_read_b128 v[194:197], v145 offset:19456
	ds_read_b128 v[198:201], v145 offset:20480
	ds_read_b128 v[202:205], v145 offset:21504
	ds_read_b128 v[236:239], v145 offset:22528
	ds_read_b128 v[240:243], v145 offset:23552
	global_load_lds_dwordx4 v[140:141], off
	s_add_i32 m0, s28, 0x2000
	s_add_u32 s36, s18, 0x40000
	v_lshl_add_u64 v[206:207], s[18:19], 0, v[130:131]
	s_addc_u32 s37, s19, 0
	s_add_i32 s28, s29, s41
	global_load_lds_dwordx4 v[206:207], off
	v_lshl_add_u64 v[228:229], s[36:37], 0, v[0:1]
	s_mov_b32 m0, s28
	v_lshl_add_u64 v[244:245], s[52:53], 0, v[132:133]
	global_load_lds_dwordx4 v[228:229], off
	v_lshl_add_u64 v[228:229], s[36:37], 0, v[130:131]
	s_add_i32 m0, s28, 0x2000
	s_nop 0
	global_load_lds_dwordx4 v[228:229], off
	v_lshl_add_u64 v[228:229], s[52:53], 0, v[134:135]
	s_mov_b32 m0, s54
	s_nop 0
	global_load_lds_dwordx4 v[228:229], off
	s_mov_b32 m0, s55
	s_nop 0
	global_load_lds_dwordx4 v[244:245], off
	s_waitcnt vmcnt(8)
	s_waitcnt lgkmcnt(0)
	s_barrier
	s_setprio 0
	s_waitcnt lgkmcnt(0)
	v_mfma_f32_16x16x32_bf16 v[62:65], v[146:149], v[182:185], v[62:65]
	v_mfma_f32_16x16x32_bf16 v[54:57], v[154:157], v[182:185], v[54:57]
	v_mfma_f32_16x16x32_bf16 v[46:49], v[146:149], v[190:193], v[46:49]
	v_mfma_f32_16x16x32_bf16 v[38:41], v[154:157], v[190:193], v[38:41]
	v_mfma_f32_16x16x32_bf16 v[30:33], v[146:149], v[198:201], v[30:33]
	v_mfma_f32_16x16x32_bf16 v[22:25], v[154:157], v[198:201], v[22:25]
	v_mfma_f32_16x16x32_bf16 v[14:17], v[146:149], v[236:239], v[14:17]
	v_mfma_f32_16x16x32_bf16 v[6:9], v[154:157], v[236:239], v[6:9]
	v_mfma_f32_16x16x32_bf16 v[62:65], v[150:153], v[186:189], v[62:65]
	v_mfma_f32_16x16x32_bf16 v[54:57], v[158:161], v[186:189], v[54:57]
	v_mfma_f32_16x16x32_bf16 v[46:49], v[150:153], v[194:197], v[46:49]
	v_mfma_f32_16x16x32_bf16 v[38:41], v[158:161], v[194:197], v[38:41]
	v_mfma_f32_16x16x32_bf16 v[30:33], v[150:153], v[202:205], v[30:33]
	v_mfma_f32_16x16x32_bf16 v[22:25], v[158:161], v[202:205], v[22:25]
	v_mfma_f32_16x16x32_bf16 v[14:17], v[150:153], v[240:243], v[14:17]
	v_mfma_f32_16x16x32_bf16 v[6:9], v[158:161], v[240:243], v[6:9]
	v_mfma_f32_16x16x32_bf16 v[58:61], v[162:165], v[182:185], v[58:61]
	v_mfma_f32_16x16x32_bf16 v[50:53], v[174:177], v[182:185], v[50:53]
	v_mfma_f32_16x16x32_bf16 v[42:45], v[162:165], v[190:193], v[42:45]
	v_mfma_f32_16x16x32_bf16 v[34:37], v[174:177], v[190:193], v[34:37]
	v_mfma_f32_16x16x32_bf16 v[26:29], v[162:165], v[198:201], v[26:29]
	v_mfma_f32_16x16x32_bf16 v[18:21], v[174:177], v[198:201], v[18:21]
	v_mfma_f32_16x16x32_bf16 v[10:13], v[162:165], v[236:239], v[10:13]
	v_mfma_f32_16x16x32_bf16 v[2:5], v[174:177], v[236:239], v[2:5]
	v_mfma_f32_16x16x32_bf16 v[58:61], v[166:169], v[186:189], v[58:61]
	v_mfma_f32_16x16x32_bf16 v[50:53], v[178:181], v[186:189], v[50:53]
	v_mfma_f32_16x16x32_bf16 v[42:45], v[166:169], v[194:197], v[42:45]
	v_mfma_f32_16x16x32_bf16 v[34:37], v[178:181], v[194:197], v[34:37]
	v_mfma_f32_16x16x32_bf16 v[26:29], v[166:169], v[202:205], v[26:29]
	v_mfma_f32_16x16x32_bf16 v[18:21], v[178:181], v[202:205], v[18:21]
	v_mfma_f32_16x16x32_bf16 v[10:13], v[166:169], v[240:243], v[10:13]
	v_mfma_f32_16x16x32_bf16 v[2:5], v[178:181], v[240:243], v[2:5]
	s_barrier
	s_setprio 1
	s_add_i32 s28, 0, 0x18000
	s_add_i32 s29, 0, 0x1c000
	v_add_u32_e32 v158, s28, v143
	v_add_u32_e32 v178, s29, v143
	ds_read_b128 v[146:149], v158
	ds_read_b128 v[150:153], v158 offset:1024
	ds_read_b128 v[154:157], v158 offset:2048
	ds_read_b128 v[158:161], v158 offset:3072
	ds_read_b128 v[162:165], v178
	ds_read_b128 v[166:169], v178 offset:1024
	ds_read_b128 v[174:177], v178 offset:2048
	ds_read_b128 v[178:181], v178 offset:3072
	s_add_u32 s36, s52, 0x40000
	s_addc_u32 s37, s53, 0
	s_mov_b32 m0, s70
	v_lshl_add_u64 v[246:247], s[36:37], 0, v[134:135]
	ds_read_b128 v[182:185], v145 offset:32768
	ds_read_b128 v[186:189], v145 offset:33792
	ds_read_b128 v[190:193], v145 offset:34816
	ds_read_b128 v[194:197], v145 offset:35840
	ds_read_b128 v[198:201], v145 offset:36864
	ds_read_b128 v[202:205], v145 offset:37888
	ds_read_b128 v[236:239], v145 offset:38912
	ds_read_b128 v[240:243], v145 offset:39936
	global_load_lds_dwordx4 v[246:247], off
	v_lshl_add_u64 v[246:247], s[36:37], 0, v[132:133]
	s_mov_b32 m0, s71
	s_nop 0
	global_load_lds_dwordx4 v[246:247], off
	s_waitcnt vmcnt(8)
	s_waitcnt lgkmcnt(0)
	s_barrier
	s_setprio 0
	s_waitcnt lgkmcnt(0)
	v_mfma_f32_16x16x32_bf16 v[126:129], v[146:149], v[182:185], v[126:129]
	v_mfma_f32_16x16x32_bf16 v[118:121], v[154:157], v[182:185], v[118:121]
	v_mfma_f32_16x16x32_bf16 v[110:113], v[146:149], v[190:193], v[110:113]
	v_mfma_f32_16x16x32_bf16 v[102:105], v[154:157], v[190:193], v[102:105]
	v_mfma_f32_16x16x32_bf16 v[94:97], v[146:149], v[198:201], v[94:97]
	v_mfma_f32_16x16x32_bf16 v[86:89], v[154:157], v[198:201], v[86:89]
	v_mfma_f32_16x16x32_bf16 v[78:81], v[146:149], v[236:239], v[78:81]
	v_mfma_f32_16x16x32_bf16 v[70:73], v[154:157], v[236:239], v[70:73]
	v_mfma_f32_16x16x32_bf16 v[126:129], v[150:153], v[186:189], v[126:129]
	v_mfma_f32_16x16x32_bf16 v[118:121], v[158:161], v[186:189], v[118:121]
	v_mfma_f32_16x16x32_bf16 v[110:113], v[150:153], v[194:197], v[110:113]
	v_mfma_f32_16x16x32_bf16 v[102:105], v[158:161], v[194:197], v[102:105]
	v_mfma_f32_16x16x32_bf16 v[94:97], v[150:153], v[202:205], v[94:97]
	v_mfma_f32_16x16x32_bf16 v[86:89], v[158:161], v[202:205], v[86:89]
	v_mfma_f32_16x16x32_bf16 v[78:81], v[150:153], v[240:243], v[78:81]
	v_mfma_f32_16x16x32_bf16 v[70:73], v[158:161], v[240:243], v[70:73]
	v_mfma_f32_16x16x32_bf16 v[122:125], v[162:165], v[182:185], v[122:125]
	v_mfma_f32_16x16x32_bf16 v[114:117], v[174:177], v[182:185], v[114:117]
	v_mfma_f32_16x16x32_bf16 v[106:109], v[162:165], v[190:193], v[106:109]
	v_mfma_f32_16x16x32_bf16 v[98:101], v[174:177], v[190:193], v[98:101]
	v_mfma_f32_16x16x32_bf16 v[90:93], v[162:165], v[198:201], v[90:93]
	v_mfma_f32_16x16x32_bf16 v[82:85], v[174:177], v[198:201], v[82:85]
	v_mfma_f32_16x16x32_bf16 v[74:77], v[162:165], v[236:239], v[74:77]
	v_mfma_f32_16x16x32_bf16 v[66:69], v[174:177], v[236:239], v[66:69]
	v_mfma_f32_16x16x32_bf16 v[122:125], v[166:169], v[186:189], v[122:125]
	v_mfma_f32_16x16x32_bf16 v[114:117], v[178:181], v[186:189], v[114:117]
	v_mfma_f32_16x16x32_bf16 v[106:109], v[166:169], v[194:197], v[106:109]
	v_mfma_f32_16x16x32_bf16 v[98:101], v[178:181], v[194:197], v[98:101]
	v_mfma_f32_16x16x32_bf16 v[90:93], v[166:169], v[202:205], v[90:93]
	v_mfma_f32_16x16x32_bf16 v[82:85], v[178:181], v[202:205], v[82:85]
	v_mfma_f32_16x16x32_bf16 v[74:77], v[166:169], v[240:243], v[74:77]
	v_mfma_f32_16x16x32_bf16 v[66:69], v[178:181], v[240:243], v[66:69]
	s_barrier
	s_setprio 1
	s_add_i32 s28, s28, s41
	v_lshl_add_u64 v[140:141], v[140:141], 0, s[4:5]
	s_mov_b32 m0, s28
	ds_read_b128 v[182:185], v145 offset:49152
	ds_read_b128 v[186:189], v145 offset:50176
	ds_read_b128 v[190:193], v145 offset:51200
	ds_read_b128 v[194:197], v145 offset:52224
	ds_read_b128 v[198:201], v145 offset:53248
	ds_read_b128 v[202:205], v145 offset:54272
	ds_read_b128 v[236:239], v145 offset:55296
	ds_read_b128 v[240:243], v145 offset:56320
	global_load_lds_dwordx4 v[140:141], off
	s_add_i32 m0, s28, 0x2000
	s_add_u32 s18, s18, 0x40080
	v_lshl_add_u64 v[140:141], v[206:207], 0, s[4:5]
	s_addc_u32 s19, s19, 0
	s_add_i32 s28, s29, s41
	global_load_lds_dwordx4 v[140:141], off
	v_lshl_add_u64 v[140:141], s[18:19], 0, v[0:1]
	s_mov_b32 m0, s28
	s_nop 0
	global_load_lds_dwordx4 v[140:141], off
	v_lshl_add_u64 v[140:141], s[18:19], 0, v[130:131]
	s_add_i32 m0, s28, 0x2000
	s_nop 0
	global_load_lds_dwordx4 v[140:141], off
	v_lshl_add_u64 v[140:141], v[228:229], 0, s[4:5]
	s_mov_b32 m0, s74
	s_nop 0
	global_load_lds_dwordx4 v[140:141], off
	v_lshl_add_u64 v[140:141], v[244:245], 0, s[4:5]
	s_mov_b32 m0, s75
	s_nop 0
	global_load_lds_dwordx4 v[140:141], off
	s_waitcnt vmcnt(8)
	s_waitcnt lgkmcnt(0)
	s_barrier
	s_setprio 0
	s_waitcnt lgkmcnt(0)
	v_mfma_f32_16x16x32_bf16 v[62:65], v[146:149], v[182:185], v[62:65]
	v_mfma_f32_16x16x32_bf16 v[54:57], v[154:157], v[182:185], v[54:57]
	v_mfma_f32_16x16x32_bf16 v[46:49], v[146:149], v[190:193], v[46:49]
	v_mfma_f32_16x16x32_bf16 v[38:41], v[154:157], v[190:193], v[38:41]
	v_mfma_f32_16x16x32_bf16 v[30:33], v[146:149], v[198:201], v[30:33]
	v_mfma_f32_16x16x32_bf16 v[22:25], v[154:157], v[198:201], v[22:25]
	v_mfma_f32_16x16x32_bf16 v[14:17], v[146:149], v[236:239], v[14:17]
	v_mfma_f32_16x16x32_bf16 v[6:9], v[154:157], v[236:239], v[6:9]
	v_mfma_f32_16x16x32_bf16 v[62:65], v[150:153], v[186:189], v[62:65]
	v_mfma_f32_16x16x32_bf16 v[54:57], v[158:161], v[186:189], v[54:57]
	v_mfma_f32_16x16x32_bf16 v[46:49], v[150:153], v[194:197], v[46:49]
	v_mfma_f32_16x16x32_bf16 v[38:41], v[158:161], v[194:197], v[38:41]
	v_mfma_f32_16x16x32_bf16 v[30:33], v[150:153], v[202:205], v[30:33]
	v_mfma_f32_16x16x32_bf16 v[22:25], v[158:161], v[202:205], v[22:25]
	v_mfma_f32_16x16x32_bf16 v[14:17], v[150:153], v[240:243], v[14:17]
	v_mfma_f32_16x16x32_bf16 v[6:9], v[158:161], v[240:243], v[6:9]
	v_mfma_f32_16x16x32_bf16 v[58:61], v[162:165], v[182:185], v[58:61]
	v_mfma_f32_16x16x32_bf16 v[50:53], v[174:177], v[182:185], v[50:53]
	v_mfma_f32_16x16x32_bf16 v[42:45], v[162:165], v[190:193], v[42:45]
	v_mfma_f32_16x16x32_bf16 v[34:37], v[174:177], v[190:193], v[34:37]
	v_mfma_f32_16x16x32_bf16 v[26:29], v[162:165], v[198:201], v[26:29]
	v_mfma_f32_16x16x32_bf16 v[18:21], v[174:177], v[198:201], v[18:21]
	v_mfma_f32_16x16x32_bf16 v[10:13], v[162:165], v[236:239], v[10:13]
	v_mfma_f32_16x16x32_bf16 v[2:5], v[174:177], v[236:239], v[2:5]
	v_mfma_f32_16x16x32_bf16 v[58:61], v[166:169], v[186:189], v[58:61]
	v_mfma_f32_16x16x32_bf16 v[50:53], v[178:181], v[186:189], v[50:53]
	v_mfma_f32_16x16x32_bf16 v[42:45], v[166:169], v[194:197], v[42:45]
	v_mfma_f32_16x16x32_bf16 v[34:37], v[178:181], v[194:197], v[34:37]
	v_mfma_f32_16x16x32_bf16 v[26:29], v[166:169], v[202:205], v[26:29]
	v_mfma_f32_16x16x32_bf16 v[18:21], v[178:181], v[202:205], v[18:21]
	v_mfma_f32_16x16x32_bf16 v[10:13], v[166:169], v[240:243], v[10:13]
	v_mfma_f32_16x16x32_bf16 v[2:5], v[178:181], v[240:243], v[2:5]
	s_barrier
	s_setprio 1
	s_add_i32 s88, s88, 2
	s_add_u32 s16, s16, 0x100
	s_addc_u32 s17, s17, 0
	s_add_u32 s83, s83, 0x100
	s_addc_u32 s85, s85, 0
	s_cmp_gt_u32 s88, 13
	s_cbranch_scc0 .LBB0_142
	s_and_b64 vcc, exec, s[12:13]
	s_cbranch_vccz .LBB0_145
	s_barrier

.LBB0_194:
	s_add_i32 vcc_lo, s12, 2
	s_add_u32 s36, s10, 0x80
	s_addc_u32 s13, s11, 0
	s_add_i32 vcc_hi, 0, 0x10000
	s_cmp_eq_u32 s94, s12
	s_cselect_b32 s13, s45, s13
	s_cselect_b32 s12, s44, s36
	s_cselect_b32 s37, s79, s15
	s_cselect_b32 s36, s78, s14
	s_add_i32 s8, 0, 0x14000
	v_add_u32_e32 v126, vcc_hi, v197
	v_add_u32_e32 v158, s8, v197
	ds_read_b128 v[114:117], v126
	ds_read_b128 v[118:121], v126 offset:1024
	ds_read_b128 v[122:125], v126 offset:2048
	ds_read_b128 v[126:129], v126 offset:3072
	ds_read_b128 v[146:149], v158
	ds_read_b128 v[150:153], v158 offset:1024
	ds_read_b128 v[154:157], v158 offset:2048
	ds_read_b128 v[158:161], v158 offset:3072
	v_lshl_add_u64 v[240:241], s[10:11], 0, v[180:181]
	s_add_i32 m0, s18, 0xc000
	ds_read_b128 v[162:165], v199
	ds_read_b128 v[166:169], v199 offset:1024
	ds_read_b128 v[184:187], v199 offset:2048
	ds_read_b128 v[188:191], v199 offset:3072
	ds_read_b128 v[192:195], v199 offset:4096
	ds_read_b128 v[200:203], v199 offset:5120
	ds_read_b128 v[204:207], v199 offset:6144
	ds_read_b128 v[236:239], v199 offset:7168
	global_load_lds_dwordx4 v[240:241], off
	v_lshl_add_u64 v[240:241], s[10:11], 0, v[182:183]
	s_add_i32 m0, s18, 0xe000
	s_nop 0
	global_load_lds_dwordx4 v[240:241], off
	s_waitcnt vmcnt(8)
	s_waitcnt lgkmcnt(0)
	s_barrier
	s_setprio 0
	s_waitcnt lgkmcnt(0)
	v_mfma_f32_16x16x32_bf16 v[142:145], v[114:117], v[162:165], v[142:145]
	v_mfma_f32_16x16x32_bf16 v[138:141], v[122:125], v[162:165], v[138:141]
	v_mfma_f32_16x16x32_bf16 v[110:113], v[114:117], v[184:187], v[110:113]
	v_mfma_f32_16x16x32_bf16 v[106:109], v[122:125], v[184:187], v[106:109]
	v_mfma_f32_16x16x32_bf16 v[94:97], v[114:117], v[192:195], v[94:97]
	v_mfma_f32_16x16x32_bf16 v[90:93], v[122:125], v[192:195], v[90:93]
	v_mfma_f32_16x16x32_bf16 v[78:81], v[114:117], v[204:207], v[78:81]
	v_mfma_f32_16x16x32_bf16 v[74:77], v[122:125], v[204:207], v[74:77]
	v_mfma_f32_16x16x32_bf16 v[142:145], v[118:121], v[166:169], v[142:145]
	v_mfma_f32_16x16x32_bf16 v[138:141], v[126:129], v[166:169], v[138:141]
	v_mfma_f32_16x16x32_bf16 v[110:113], v[118:121], v[188:191], v[110:113]
	v_mfma_f32_16x16x32_bf16 v[106:109], v[126:129], v[188:191], v[106:109]
	v_mfma_f32_16x16x32_bf16 v[94:97], v[118:121], v[200:203], v[94:97]
	v_mfma_f32_16x16x32_bf16 v[90:93], v[126:129], v[200:203], v[90:93]
	v_mfma_f32_16x16x32_bf16 v[78:81], v[118:121], v[236:239], v[78:81]
	v_mfma_f32_16x16x32_bf16 v[74:77], v[126:129], v[236:239], v[74:77]
	v_mfma_f32_16x16x32_bf16 v[134:137], v[146:149], v[162:165], v[134:137]
	v_mfma_f32_16x16x32_bf16 v[130:133], v[154:157], v[162:165], v[130:133]
	v_mfma_f32_16x16x32_bf16 v[102:105], v[146:149], v[184:187], v[102:105]
	v_mfma_f32_16x16x32_bf16 v[98:101], v[154:157], v[184:187], v[98:101]
	v_mfma_f32_16x16x32_bf16 v[86:89], v[146:149], v[192:195], v[86:89]
	v_mfma_f32_16x16x32_bf16 v[82:85], v[154:157], v[192:195], v[82:85]
	v_mfma_f32_16x16x32_bf16 v[70:73], v[146:149], v[204:207], v[70:73]
	v_mfma_f32_16x16x32_bf16 v[66:69], v[154:157], v[204:207], v[66:69]
	v_mfma_f32_16x16x32_bf16 v[134:137], v[150:153], v[166:169], v[134:137]
	v_mfma_f32_16x16x32_bf16 v[130:133], v[158:161], v[166:169], v[130:133]
	v_mfma_f32_16x16x32_bf16 v[102:105], v[150:153], v[188:191], v[102:105]
	v_mfma_f32_16x16x32_bf16 v[98:101], v[158:161], v[188:191], v[98:101]
	v_mfma_f32_16x16x32_bf16 v[86:89], v[150:153], v[200:203], v[86:89]
	v_mfma_f32_16x16x32_bf16 v[82:85], v[158:161], v[200:203], v[82:85]
	v_mfma_f32_16x16x32_bf16 v[70:73], v[150:153], v[236:239], v[70:73]
	v_mfma_f32_16x16x32_bf16 v[66:69], v[158:161], v[236:239], v[66:69]
	s_barrier
	s_setprio 1
	s_add_i32 s9, vcc_hi, s17
	v_lshl_add_u64 v[240:241], s[36:37], 0, v[0:1]
	s_mov_b32 m0, s9
	ds_read_b128 v[162:165], v199 offset:16384
	ds_read_b128 v[166:169], v199 offset:17408
	ds_read_b128 v[184:187], v199 offset:18432
	ds_read_b128 v[188:191], v199 offset:19456
	ds_read_b128 v[192:195], v199 offset:20480
	ds_read_b128 v[200:203], v199 offset:21504
	ds_read_b128 v[204:207], v199 offset:22528
	ds_read_b128 v[236:239], v199 offset:23552
	global_load_lds_dwordx4 v[240:241], off
	s_add_i32 m0, s9, 0x2000
	v_lshl_add_u64 v[242:243], s[36:37], 0, v[174:175]
	s_add_u32 s36, s36, s20
	s_addc_u32 s37, s37, 0
	s_add_i32 s8, s8, s17
	global_load_lds_dwordx4 v[242:243], off
	v_lshl_add_u64 v[244:245], s[36:37], 0, v[0:1]
	s_mov_b32 m0, s8
	v_lshl_add_u64 v[246:247], s[36:37], 0, v[174:175]
	global_load_lds_dwordx4 v[244:245], off
	s_add_i32 m0, s8, 0x2000
	v_lshl_add_u64 v[248:249], s[12:13], 0, v[178:179]
	global_load_lds_dwordx4 v[246:247], off
	s_mov_b32 m0, s18
	v_lshl_add_u64 v[250:251], s[12:13], 0, v[176:177]
	global_load_lds_dwordx4 v[248:249], off
	s_mov_b32 m0, s19
	s_nop 0
	global_load_lds_dwordx4 v[250:251], off
	s_waitcnt vmcnt(8)
	s_waitcnt lgkmcnt(0)
	s_barrier
	s_setprio 0
	s_waitcnt lgkmcnt(0)
	v_mfma_f32_16x16x32_bf16 v[62:65], v[114:117], v[162:165], v[62:65]
	v_mfma_f32_16x16x32_bf16 v[58:61], v[122:125], v[162:165], v[58:61]
	v_mfma_f32_16x16x32_bf16 v[46:49], v[114:117], v[184:187], v[46:49]
	v_mfma_f32_16x16x32_bf16 v[42:45], v[122:125], v[184:187], v[42:45]
	v_mfma_f32_16x16x32_bf16 v[30:33], v[114:117], v[192:195], v[30:33]
	v_mfma_f32_16x16x32_bf16 v[26:29], v[122:125], v[192:195], v[26:29]
	v_mfma_f32_16x16x32_bf16 v[14:17], v[114:117], v[204:207], v[14:17]
	v_mfma_f32_16x16x32_bf16 v[10:13], v[122:125], v[204:207], v[10:13]
	v_mfma_f32_16x16x32_bf16 v[62:65], v[118:121], v[166:169], v[62:65]
	v_mfma_f32_16x16x32_bf16 v[58:61], v[126:129], v[166:169], v[58:61]
	v_mfma_f32_16x16x32_bf16 v[46:49], v[118:121], v[188:191], v[46:49]
	v_mfma_f32_16x16x32_bf16 v[42:45], v[126:129], v[188:191], v[42:45]
	v_mfma_f32_16x16x32_bf16 v[30:33], v[118:121], v[200:203], v[30:33]
	v_mfma_f32_16x16x32_bf16 v[26:29], v[126:129], v[200:203], v[26:29]
	v_mfma_f32_16x16x32_bf16 v[14:17], v[118:121], v[236:239], v[14:17]
	v_mfma_f32_16x16x32_bf16 v[10:13], v[126:129], v[236:239], v[10:13]
	v_mfma_f32_16x16x32_bf16 v[54:57], v[146:149], v[162:165], v[54:57]
	v_mfma_f32_16x16x32_bf16 v[50:53], v[154:157], v[162:165], v[50:53]
	v_mfma_f32_16x16x32_bf16 v[38:41], v[146:149], v[184:187], v[38:41]
	v_mfma_f32_16x16x32_bf16 v[34:37], v[154:157], v[184:187], v[34:37]
	v_mfma_f32_16x16x32_bf16 v[22:25], v[146:149], v[192:195], v[22:25]
	v_mfma_f32_16x16x32_bf16 v[18:21], v[154:157], v[192:195], v[18:21]
	v_mfma_f32_16x16x32_bf16 v[6:9], v[146:149], v[204:207], v[6:9]
	v_mfma_f32_16x16x32_bf16 v[2:5], v[154:157], v[204:207], v[2:5]
	v_mfma_f32_16x16x32_bf16 v[54:57], v[150:153], v[166:169], v[54:57]
	v_mfma_f32_16x16x32_bf16 v[50:53], v[158:161], v[166:169], v[50:53]
	v_mfma_f32_16x16x32_bf16 v[38:41], v[150:153], v[188:191], v[38:41]
	v_mfma_f32_16x16x32_bf16 v[34:37], v[158:161], v[188:191], v[34:37]
	v_mfma_f32_16x16x32_bf16 v[22:25], v[150:153], v[200:203], v[22:25]
	v_mfma_f32_16x16x32_bf16 v[18:21], v[158:161], v[200:203], v[18:21]
	v_mfma_f32_16x16x32_bf16 v[6:9], v[150:153], v[236:239], v[6:9]
	v_mfma_f32_16x16x32_bf16 v[2:5], v[158:161], v[236:239], v[2:5]
	s_barrier
	s_setprio 1
	s_add_i32 s8, 0, 0x18000
	s_add_i32 s9, 0, 0x1c000
	v_add_u32_e32 v126, s8, v197
	v_add_u32_e32 v158, s9, v197
	ds_read_b128 v[114:117], v126
	ds_read_b128 v[118:121], v126 offset:1024
	ds_read_b128 v[122:125], v126 offset:2048
	ds_read_b128 v[126:129], v126 offset:3072
	ds_read_b128 v[146:149], v158
	ds_read_b128 v[150:153], v158 offset:1024
	ds_read_b128 v[154:157], v158 offset:2048
	ds_read_b128 v[158:161], v158 offset:3072
	s_add_u32 s12, s12, s20
	s_addc_u32 s13, s13, 0
	s_mov_b32 m0, s70
	v_lshl_add_u64 v[228:229], s[12:13], 0, v[178:179]
	ds_read_b128 v[162:165], v199 offset:32768
	ds_read_b128 v[166:169], v199 offset:33792
	ds_read_b128 v[184:187], v199 offset:34816
	ds_read_b128 v[188:191], v199 offset:35840
	ds_read_b128 v[192:195], v199 offset:36864
	ds_read_b128 v[200:203], v199 offset:37888
	ds_read_b128 v[204:207], v199 offset:38912
	ds_read_b128 v[236:239], v199 offset:39936
	global_load_lds_dwordx4 v[228:229], off
	v_lshl_add_u64 v[228:229], s[12:13], 0, v[176:177]
	s_mov_b32 m0, s71
	s_nop 0
	global_load_lds_dwordx4 v[228:229], off
	s_waitcnt vmcnt(8)
	s_waitcnt lgkmcnt(0)
	s_barrier
	s_setprio 0
	s_waitcnt lgkmcnt(0)
	v_mfma_f32_16x16x32_bf16 v[142:145], v[114:117], v[162:165], v[142:145]
	v_mfma_f32_16x16x32_bf16 v[138:141], v[122:125], v[162:165], v[138:141]
	v_mfma_f32_16x16x32_bf16 v[110:113], v[114:117], v[184:187], v[110:113]
	v_mfma_f32_16x16x32_bf16 v[106:109], v[122:125], v[184:187], v[106:109]
	v_mfma_f32_16x16x32_bf16 v[94:97], v[114:117], v[192:195], v[94:97]
	v_mfma_f32_16x16x32_bf16 v[90:93], v[122:125], v[192:195], v[90:93]
	v_mfma_f32_16x16x32_bf16 v[78:81], v[114:117], v[204:207], v[78:81]
	v_mfma_f32_16x16x32_bf16 v[74:77], v[122:125], v[204:207], v[74:77]
	v_mfma_f32_16x16x32_bf16 v[142:145], v[118:121], v[166:169], v[142:145]
	v_mfma_f32_16x16x32_bf16 v[138:141], v[126:129], v[166:169], v[138:141]
	v_mfma_f32_16x16x32_bf16 v[110:113], v[118:121], v[188:191], v[110:113]
	v_mfma_f32_16x16x32_bf16 v[106:109], v[126:129], v[188:191], v[106:109]
	v_mfma_f32_16x16x32_bf16 v[94:97], v[118:121], v[200:203], v[94:97]
	v_mfma_f32_16x16x32_bf16 v[90:93], v[126:129], v[200:203], v[90:93]
	v_mfma_f32_16x16x32_bf16 v[78:81], v[118:121], v[236:239], v[78:81]
	v_mfma_f32_16x16x32_bf16 v[74:77], v[126:129], v[236:239], v[74:77]
	v_mfma_f32_16x16x32_bf16 v[134:137], v[146:149], v[162:165], v[134:137]
	v_mfma_f32_16x16x32_bf16 v[130:133], v[154:157], v[162:165], v[130:133]
	v_mfma_f32_16x16x32_bf16 v[102:105], v[146:149], v[184:187], v[102:105]
	v_mfma_f32_16x16x32_bf16 v[98:101], v[154:157], v[184:187], v[98:101]
	v_mfma_f32_16x16x32_bf16 v[86:89], v[146:149], v[192:195], v[86:89]
	v_mfma_f32_16x16x32_bf16 v[82:85], v[154:157], v[192:195], v[82:85]
	v_mfma_f32_16x16x32_bf16 v[70:73], v[146:149], v[204:207], v[70:73]
	v_mfma_f32_16x16x32_bf16 v[66:69], v[154:157], v[204:207], v[66:69]
	v_mfma_f32_16x16x32_bf16 v[134:137], v[150:153], v[166:169], v[134:137]
	v_mfma_f32_16x16x32_bf16 v[130:133], v[158:161], v[166:169], v[130:133]
	v_mfma_f32_16x16x32_bf16 v[102:105], v[150:153], v[188:191], v[102:105]
	v_mfma_f32_16x16x32_bf16 v[98:101], v[158:161], v[188:191], v[98:101]
	v_mfma_f32_16x16x32_bf16 v[86:89], v[150:153], v[200:203], v[86:89]
	v_mfma_f32_16x16x32_bf16 v[82:85], v[158:161], v[200:203], v[82:85]
	v_mfma_f32_16x16x32_bf16 v[70:73], v[150:153], v[236:239], v[70:73]
	v_mfma_f32_16x16x32_bf16 v[66:69], v[158:161], v[236:239], v[66:69]
	s_barrier
	s_setprio 1
	s_add_i32 s8, s8, s17
	v_lshl_add_u64 v[228:229], v[240:241], 0, s[4:5]
	s_mov_b32 m0, s8
	ds_read_b128 v[162:165], v199 offset:49152
	ds_read_b128 v[166:169], v199 offset:50176
	ds_read_b128 v[184:187], v199 offset:51200
	ds_read_b128 v[188:191], v199 offset:52224
	ds_read_b128 v[192:195], v199 offset:53248
	ds_read_b128 v[200:203], v199 offset:54272
	ds_read_b128 v[204:207], v199 offset:55296
	ds_read_b128 v[236:239], v199 offset:56320
	global_load_lds_dwordx4 v[228:229], off
	v_lshl_add_u64 v[228:229], v[242:243], 0, s[4:5]
	s_add_i32 m0, s8, 0x2000
	s_add_i32 s8, s9, s17
	global_load_lds_dwordx4 v[228:229], off
	v_lshl_add_u64 v[228:229], v[244:245], 0, s[4:5]
	s_mov_b32 m0, s8
	s_nop 0
	global_load_lds_dwordx4 v[228:229], off
	v_lshl_add_u64 v[228:229], v[246:247], 0, s[4:5]
	s_add_i32 m0, s8, 0x2000
	s_nop 0
	global_load_lds_dwordx4 v[228:229], off
	v_lshl_add_u64 v[228:229], v[248:249], 0, s[4:5]
	s_mov_b32 m0, s88
	s_nop 0
	global_load_lds_dwordx4 v[228:229], off
	v_lshl_add_u64 v[228:229], v[250:251], 0, s[4:5]
	s_mov_b32 m0, s89
	s_nop 0
	global_load_lds_dwordx4 v[228:229], off
	s_waitcnt vmcnt(8)
	s_waitcnt lgkmcnt(0)
	s_barrier
	s_setprio 0
	s_waitcnt lgkmcnt(0)
	v_mfma_f32_16x16x32_bf16 v[62:65], v[114:117], v[162:165], v[62:65]
	v_mfma_f32_16x16x32_bf16 v[58:61], v[122:125], v[162:165], v[58:61]
	v_mfma_f32_16x16x32_bf16 v[46:49], v[114:117], v[184:187], v[46:49]
	v_mfma_f32_16x16x32_bf16 v[42:45], v[122:125], v[184:187], v[42:45]
	v_mfma_f32_16x16x32_bf16 v[30:33], v[114:117], v[192:195], v[30:33]
	v_mfma_f32_16x16x32_bf16 v[26:29], v[122:125], v[192:195], v[26:29]
	v_mfma_f32_16x16x32_bf16 v[14:17], v[114:117], v[204:207], v[14:17]
	v_mfma_f32_16x16x32_bf16 v[10:13], v[122:125], v[204:207], v[10:13]
	v_mfma_f32_16x16x32_bf16 v[62:65], v[118:121], v[166:169], v[62:65]
	v_mfma_f32_16x16x32_bf16 v[58:61], v[126:129], v[166:169], v[58:61]
	v_mfma_f32_16x16x32_bf16 v[46:49], v[118:121], v[188:191], v[46:49]
	v_mfma_f32_16x16x32_bf16 v[42:45], v[126:129], v[188:191], v[42:45]
	v_mfma_f32_16x16x32_bf16 v[30:33], v[118:121], v[200:203], v[30:33]
	v_mfma_f32_16x16x32_bf16 v[26:29], v[126:129], v[200:203], v[26:29]
	v_mfma_f32_16x16x32_bf16 v[14:17], v[118:121], v[236:239], v[14:17]
	v_mfma_f32_16x16x32_bf16 v[10:13], v[126:129], v[236:239], v[10:13]
	v_mfma_f32_16x16x32_bf16 v[54:57], v[146:149], v[162:165], v[54:57]
	v_mfma_f32_16x16x32_bf16 v[50:53], v[154:157], v[162:165], v[50:53]
	v_mfma_f32_16x16x32_bf16 v[38:41], v[146:149], v[184:187], v[38:41]
	v_mfma_f32_16x16x32_bf16 v[34:37], v[154:157], v[184:187], v[34:37]
	v_mfma_f32_16x16x32_bf16 v[22:25], v[146:149], v[192:195], v[22:25]
	v_mfma_f32_16x16x32_bf16 v[18:21], v[154:157], v[192:195], v[18:21]
	v_mfma_f32_16x16x32_bf16 v[6:9], v[146:149], v[204:207], v[6:9]
	v_mfma_f32_16x16x32_bf16 v[2:5], v[154:157], v[204:207], v[2:5]
	v_mfma_f32_16x16x32_bf16 v[54:57], v[150:153], v[166:169], v[54:57]
	v_mfma_f32_16x16x32_bf16 v[50:53], v[158:161], v[166:169], v[50:53]
	v_mfma_f32_16x16x32_bf16 v[38:41], v[150:153], v[188:191], v[38:41]
	v_mfma_f32_16x16x32_bf16 v[34:37], v[158:161], v[188:191], v[34:37]
	v_mfma_f32_16x16x32_bf16 v[22:25], v[150:153], v[200:203], v[22:25]
	v_mfma_f32_16x16x32_bf16 v[18:21], v[158:161], v[200:203], v[18:21]
	v_mfma_f32_16x16x32_bf16 v[6:9], v[150:153], v[236:239], v[6:9]
	v_mfma_f32_16x16x32_bf16 v[2:5], v[158:161], v[236:239], v[2:5]
	s_barrier
	s_setprio 1
	s_add_u32 s10, s10, 0x100
	s_addc_u32 s11, s11, 0
	s_add_u32 s14, s14, 0x100
	s_addc_u32 s15, s15, 0
	s_cmp_ge_u32 vcc_lo, s77
	s_mov_b32 s12, vcc_lo
	s_cbranch_scc0 .LBB0_194
	s_and_b64 vcc, exec, s[54:55]
	s_cbranch_vccz .LBB0_197
	s_barrier

.LBB0_219:
	s_add_i32 vcc_lo, s48, 2
	s_add_u32 s36, s18, 0x80
	s_addc_u32 s37, s19, 0
	s_add_i32 vcc_hi, 0, 0x10000
	s_cmp_eq_u32 s89, s48
	s_cselect_b32 s49, s17, s37
	s_cselect_b32 s48, s16, s36
	s_cselect_b32 s37, s45, s15
	s_cselect_b32 s36, s44, s11
	s_add_i32 s28, 0, 0x14000
	v_add_u32_e32 v156, vcc_hi, v141
	v_add_u32_e32 v168, s28, v141
	ds_read_b128 v[144:147], v156
	ds_read_b128 v[148:151], v156 offset:1024
	ds_read_b128 v[152:155], v156 offset:2048
	ds_read_b128 v[156:159], v156 offset:3072
	ds_read_b128 v[160:163], v168
	ds_read_b128 v[164:167], v168 offset:1024
	ds_read_b128 v[174:177], v168 offset:2048
	ds_read_b128 v[178:181], v168 offset:3072
	v_lshl_add_u64 v[168:169], s[18:19], 0, v[136:137]
	s_add_i32 m0, s54, 0xc000
	ds_read_b128 v[182:185], v143
	ds_read_b128 v[186:189], v143 offset:1024
	ds_read_b128 v[190:193], v143 offset:2048
	ds_read_b128 v[194:197], v143 offset:3072
	ds_read_b128 v[198:201], v143 offset:4096
	ds_read_b128 v[202:205], v143 offset:5120
	ds_read_b128 v[236:239], v143 offset:6144
	ds_read_b128 v[240:243], v143 offset:7168
	global_load_lds_dwordx4 v[168:169], off
	v_lshl_add_u64 v[168:169], s[18:19], 0, v[138:139]
	s_add_i32 m0, s54, 0xe000
	s_nop 0
	global_load_lds_dwordx4 v[168:169], off
	s_waitcnt vmcnt(8)
	s_waitcnt lgkmcnt(0)
	s_barrier
	s_setprio 0
	s_waitcnt lgkmcnt(0)
	v_mfma_f32_16x16x32_bf16 v[126:129], v[144:147], v[182:185], v[126:129]
	v_mfma_f32_16x16x32_bf16 v[122:125], v[152:155], v[182:185], v[122:125]
	v_mfma_f32_16x16x32_bf16 v[118:121], v[144:147], v[190:193], v[118:121]
	v_mfma_f32_16x16x32_bf16 v[114:117], v[152:155], v[190:193], v[114:117]
	v_mfma_f32_16x16x32_bf16 v[106:109], v[144:147], v[198:201], v[106:109]
	v_mfma_f32_16x16x32_bf16 v[98:101], v[152:155], v[198:201], v[98:101]
	v_mfma_f32_16x16x32_bf16 v[90:93], v[144:147], v[236:239], v[90:93]
	v_mfma_f32_16x16x32_bf16 v[82:85], v[152:155], v[236:239], v[82:85]
	v_mfma_f32_16x16x32_bf16 v[126:129], v[148:151], v[186:189], v[126:129]
	v_mfma_f32_16x16x32_bf16 v[122:125], v[156:159], v[186:189], v[122:125]
	v_mfma_f32_16x16x32_bf16 v[118:121], v[148:151], v[194:197], v[118:121]
	v_mfma_f32_16x16x32_bf16 v[114:117], v[156:159], v[194:197], v[114:117]
	v_mfma_f32_16x16x32_bf16 v[106:109], v[148:151], v[202:205], v[106:109]
	v_mfma_f32_16x16x32_bf16 v[98:101], v[156:159], v[202:205], v[98:101]
	v_mfma_f32_16x16x32_bf16 v[90:93], v[148:151], v[240:243], v[90:93]
	v_mfma_f32_16x16x32_bf16 v[82:85], v[156:159], v[240:243], v[82:85]
	v_mfma_f32_16x16x32_bf16 v[110:113], v[160:163], v[182:185], v[110:113]
	v_mfma_f32_16x16x32_bf16 v[102:105], v[174:177], v[182:185], v[102:105]
	v_mfma_f32_16x16x32_bf16 v[94:97], v[160:163], v[190:193], v[94:97]
	v_mfma_f32_16x16x32_bf16 v[86:89], v[174:177], v[190:193], v[86:89]
	v_mfma_f32_16x16x32_bf16 v[78:81], v[160:163], v[198:201], v[78:81]
	v_mfma_f32_16x16x32_bf16 v[74:77], v[174:177], v[198:201], v[74:77]
	v_mfma_f32_16x16x32_bf16 v[70:73], v[160:163], v[236:239], v[70:73]
	v_mfma_f32_16x16x32_bf16 v[66:69], v[174:177], v[236:239], v[66:69]
	v_mfma_f32_16x16x32_bf16 v[110:113], v[164:167], v[186:189], v[110:113]
	v_mfma_f32_16x16x32_bf16 v[102:105], v[178:181], v[186:189], v[102:105]
	v_mfma_f32_16x16x32_bf16 v[94:97], v[164:167], v[194:197], v[94:97]
	v_mfma_f32_16x16x32_bf16 v[86:89], v[178:181], v[194:197], v[86:89]
	v_mfma_f32_16x16x32_bf16 v[78:81], v[164:167], v[202:205], v[78:81]
	v_mfma_f32_16x16x32_bf16 v[74:77], v[178:181], v[202:205], v[74:77]
	v_mfma_f32_16x16x32_bf16 v[70:73], v[164:167], v[240:243], v[70:73]
	v_mfma_f32_16x16x32_bf16 v[66:69], v[178:181], v[240:243], v[66:69]
	s_barrier
	s_setprio 1
	s_add_i32 s29, vcc_hi, s41
	v_lshl_add_u64 v[168:169], s[36:37], 0, v[0:1]
	s_mov_b32 m0, s29
	ds_read_b128 v[182:185], v143 offset:16384
	ds_read_b128 v[186:189], v143 offset:17408
	ds_read_b128 v[190:193], v143 offset:18432
	ds_read_b128 v[194:197], v143 offset:19456
	ds_read_b128 v[198:201], v143 offset:20480
	ds_read_b128 v[202:205], v143 offset:21504
	ds_read_b128 v[236:239], v143 offset:22528
	ds_read_b128 v[240:243], v143 offset:23552
	global_load_lds_dwordx4 v[168:169], off
	s_add_i32 m0, s29, 0x2000
	v_lshl_add_u64 v[206:207], s[36:37], 0, v[130:131]
	s_add_u32 s36, s36, s20
	s_addc_u32 s37, s37, 0
	s_add_i32 s28, s28, s41
	global_load_lds_dwordx4 v[206:207], off
	v_lshl_add_u64 v[228:229], s[36:37], 0, v[0:1]
	s_mov_b32 m0, s28
	v_lshl_add_u64 v[244:245], s[36:37], 0, v[130:131]
	global_load_lds_dwordx4 v[228:229], off
	s_add_i32 m0, s28, 0x2000
	v_lshl_add_u64 v[246:247], s[48:49], 0, v[134:135]
	global_load_lds_dwordx4 v[244:245], off
	s_mov_b32 m0, s54
	v_lshl_add_u64 v[248:249], s[48:49], 0, v[132:133]
	global_load_lds_dwordx4 v[246:247], off
	s_mov_b32 m0, s55
	s_nop 0
	global_load_lds_dwordx4 v[248:249], off
	s_waitcnt vmcnt(8)
	s_waitcnt lgkmcnt(0)
	s_barrier
	s_setprio 0
	s_waitcnt lgkmcnt(0)
	v_mfma_f32_16x16x32_bf16 v[62:65], v[144:147], v[182:185], v[62:65]
	v_mfma_f32_16x16x32_bf16 v[58:61], v[152:155], v[182:185], v[58:61]
	v_mfma_f32_16x16x32_bf16 v[54:57], v[144:147], v[190:193], v[54:57]
	v_mfma_f32_16x16x32_bf16 v[50:53], v[152:155], v[190:193], v[50:53]
	v_mfma_f32_16x16x32_bf16 v[42:45], v[144:147], v[198:201], v[42:45]
	v_mfma_f32_16x16x32_bf16 v[34:37], v[152:155], v[198:201], v[34:37]
	v_mfma_f32_16x16x32_bf16 v[26:29], v[144:147], v[236:239], v[26:29]
	v_mfma_f32_16x16x32_bf16 v[18:21], v[152:155], v[236:239], v[18:21]
	v_mfma_f32_16x16x32_bf16 v[62:65], v[148:151], v[186:189], v[62:65]
	v_mfma_f32_16x16x32_bf16 v[58:61], v[156:159], v[186:189], v[58:61]
	v_mfma_f32_16x16x32_bf16 v[54:57], v[148:151], v[194:197], v[54:57]
	v_mfma_f32_16x16x32_bf16 v[50:53], v[156:159], v[194:197], v[50:53]
	v_mfma_f32_16x16x32_bf16 v[42:45], v[148:151], v[202:205], v[42:45]
	v_mfma_f32_16x16x32_bf16 v[34:37], v[156:159], v[202:205], v[34:37]
	v_mfma_f32_16x16x32_bf16 v[26:29], v[148:151], v[240:243], v[26:29]
	v_mfma_f32_16x16x32_bf16 v[18:21], v[156:159], v[240:243], v[18:21]
	v_mfma_f32_16x16x32_bf16 v[46:49], v[160:163], v[182:185], v[46:49]
	v_mfma_f32_16x16x32_bf16 v[38:41], v[174:177], v[182:185], v[38:41]
	v_mfma_f32_16x16x32_bf16 v[30:33], v[160:163], v[190:193], v[30:33]
	v_mfma_f32_16x16x32_bf16 v[22:25], v[174:177], v[190:193], v[22:25]
	v_mfma_f32_16x16x32_bf16 v[14:17], v[160:163], v[198:201], v[14:17]
	v_mfma_f32_16x16x32_bf16 v[10:13], v[174:177], v[198:201], v[10:13]
	v_mfma_f32_16x16x32_bf16 v[6:9], v[160:163], v[236:239], v[6:9]
	v_mfma_f32_16x16x32_bf16 v[2:5], v[174:177], v[236:239], v[2:5]
	v_mfma_f32_16x16x32_bf16 v[46:49], v[164:167], v[186:189], v[46:49]
	v_mfma_f32_16x16x32_bf16 v[38:41], v[178:181], v[186:189], v[38:41]
	v_mfma_f32_16x16x32_bf16 v[30:33], v[164:167], v[194:197], v[30:33]
	v_mfma_f32_16x16x32_bf16 v[22:25], v[178:181], v[194:197], v[22:25]
	v_mfma_f32_16x16x32_bf16 v[14:17], v[164:167], v[202:205], v[14:17]
	v_mfma_f32_16x16x32_bf16 v[10:13], v[178:181], v[202:205], v[10:13]
	v_mfma_f32_16x16x32_bf16 v[6:9], v[164:167], v[240:243], v[6:9]
	v_mfma_f32_16x16x32_bf16 v[2:5], v[178:181], v[240:243], v[2:5]
	s_barrier
	s_setprio 1
	s_add_i32 s28, 0, 0x18000
	s_add_i32 s29, 0, 0x1c000
	v_add_u32_e32 v156, s28, v141
	v_add_u32_e32 v178, s29, v141
	ds_read_b128 v[144:147], v156
	ds_read_b128 v[148:151], v156 offset:1024
	ds_read_b128 v[152:155], v156 offset:2048
	ds_read_b128 v[156:159], v156 offset:3072
	ds_read_b128 v[160:163], v178
	ds_read_b128 v[164:167], v178 offset:1024
	ds_read_b128 v[174:177], v178 offset:2048
	ds_read_b128 v[178:181], v178 offset:3072
	s_add_u32 s36, s48, s20
	s_addc_u32 s37, s49, 0
	s_mov_b32 m0, s70
	v_lshl_add_u64 v[250:251], s[36:37], 0, v[134:135]
	ds_read_b128 v[182:185], v143 offset:32768
	ds_read_b128 v[186:189], v143 offset:33792
	ds_read_b128 v[190:193], v143 offset:34816
	ds_read_b128 v[194:197], v143 offset:35840
	ds_read_b128 v[198:201], v143 offset:36864
	ds_read_b128 v[202:205], v143 offset:37888
	ds_read_b128 v[236:239], v143 offset:38912
	ds_read_b128 v[240:243], v143 offset:39936
	global_load_lds_dwordx4 v[250:251], off
	v_lshl_add_u64 v[250:251], s[36:37], 0, v[132:133]
	s_mov_b32 m0, s71
	s_nop 0
	global_load_lds_dwordx4 v[250:251], off
	s_waitcnt vmcnt(8)
	s_waitcnt lgkmcnt(0)
	s_barrier
	s_setprio 0
	s_waitcnt lgkmcnt(0)
	v_mfma_f32_16x16x32_bf16 v[126:129], v[144:147], v[182:185], v[126:129]
	v_mfma_f32_16x16x32_bf16 v[122:125], v[152:155], v[182:185], v[122:125]
	v_mfma_f32_16x16x32_bf16 v[118:121], v[144:147], v[190:193], v[118:121]
	v_mfma_f32_16x16x32_bf16 v[114:117], v[152:155], v[190:193], v[114:117]
	v_mfma_f32_16x16x32_bf16 v[106:109], v[144:147], v[198:201], v[106:109]
	v_mfma_f32_16x16x32_bf16 v[98:101], v[152:155], v[198:201], v[98:101]
	v_mfma_f32_16x16x32_bf16 v[90:93], v[144:147], v[236:239], v[90:93]
	v_mfma_f32_16x16x32_bf16 v[82:85], v[152:155], v[236:239], v[82:85]
	v_mfma_f32_16x16x32_bf16 v[126:129], v[148:151], v[186:189], v[126:129]
	v_mfma_f32_16x16x32_bf16 v[122:125], v[156:159], v[186:189], v[122:125]
	v_mfma_f32_16x16x32_bf16 v[118:121], v[148:151], v[194:197], v[118:121]
	v_mfma_f32_16x16x32_bf16 v[114:117], v[156:159], v[194:197], v[114:117]
	v_mfma_f32_16x16x32_bf16 v[106:109], v[148:151], v[202:205], v[106:109]
	v_mfma_f32_16x16x32_bf16 v[98:101], v[156:159], v[202:205], v[98:101]
	v_mfma_f32_16x16x32_bf16 v[90:93], v[148:151], v[240:243], v[90:93]
	v_mfma_f32_16x16x32_bf16 v[82:85], v[156:159], v[240:243], v[82:85]
	v_mfma_f32_16x16x32_bf16 v[110:113], v[160:163], v[182:185], v[110:113]
	v_mfma_f32_16x16x32_bf16 v[102:105], v[174:177], v[182:185], v[102:105]
	v_mfma_f32_16x16x32_bf16 v[94:97], v[160:163], v[190:193], v[94:97]
	v_mfma_f32_16x16x32_bf16 v[86:89], v[174:177], v[190:193], v[86:89]
	v_mfma_f32_16x16x32_bf16 v[78:81], v[160:163], v[198:201], v[78:81]
	v_mfma_f32_16x16x32_bf16 v[74:77], v[174:177], v[198:201], v[74:77]
	v_mfma_f32_16x16x32_bf16 v[70:73], v[160:163], v[236:239], v[70:73]
	v_mfma_f32_16x16x32_bf16 v[66:69], v[174:177], v[236:239], v[66:69]
	v_mfma_f32_16x16x32_bf16 v[110:113], v[164:167], v[186:189], v[110:113]
	v_mfma_f32_16x16x32_bf16 v[102:105], v[178:181], v[186:189], v[102:105]
	v_mfma_f32_16x16x32_bf16 v[94:97], v[164:167], v[194:197], v[94:97]
	v_mfma_f32_16x16x32_bf16 v[86:89], v[178:181], v[194:197], v[86:89]
	v_mfma_f32_16x16x32_bf16 v[78:81], v[164:167], v[202:205], v[78:81]
	v_mfma_f32_16x16x32_bf16 v[74:77], v[178:181], v[202:205], v[74:77]
	v_mfma_f32_16x16x32_bf16 v[70:73], v[164:167], v[240:243], v[70:73]
	v_mfma_f32_16x16x32_bf16 v[66:69], v[178:181], v[240:243], v[66:69]
	s_barrier
	s_setprio 1
	s_add_i32 s28, s28, s41
	v_lshl_add_u64 v[168:169], v[168:169], 0, s[4:5]
	s_mov_b32 m0, s28
	ds_read_b128 v[182:185], v143 offset:49152
	ds_read_b128 v[186:189], v143 offset:50176
	ds_read_b128 v[190:193], v143 offset:51200
	ds_read_b128 v[194:197], v143 offset:52224
	ds_read_b128 v[198:201], v143 offset:53248
	ds_read_b128 v[202:205], v143 offset:54272
	ds_read_b128 v[236:239], v143 offset:55296
	ds_read_b128 v[240:243], v143 offset:56320
	global_load_lds_dwordx4 v[168:169], off
	v_lshl_add_u64 v[168:169], v[206:207], 0, s[4:5]
	s_add_i32 m0, s28, 0x2000
	s_add_i32 s28, s29, s41
	global_load_lds_dwordx4 v[168:169], off
	v_lshl_add_u64 v[168:169], v[228:229], 0, s[4:5]
	s_mov_b32 m0, s28
	s_nop 0
	global_load_lds_dwordx4 v[168:169], off
	v_lshl_add_u64 v[168:169], v[244:245], 0, s[4:5]
	s_add_i32 m0, s28, 0x2000
	s_nop 0
	global_load_lds_dwordx4 v[168:169], off
	v_lshl_add_u64 v[168:169], v[246:247], 0, s[4:5]
	s_mov_b32 m0, s83
	s_nop 0
	global_load_lds_dwordx4 v[168:169], off
	v_lshl_add_u64 v[168:169], v[248:249], 0, s[4:5]
	s_mov_b32 m0, s85
	s_nop 0
	global_load_lds_dwordx4 v[168:169], off
	s_waitcnt vmcnt(8)
	s_waitcnt lgkmcnt(0)
	s_barrier
	s_setprio 0
	s_waitcnt lgkmcnt(0)
	v_mfma_f32_16x16x32_bf16 v[62:65], v[144:147], v[182:185], v[62:65]
	v_mfma_f32_16x16x32_bf16 v[58:61], v[152:155], v[182:185], v[58:61]
	v_mfma_f32_16x16x32_bf16 v[54:57], v[144:147], v[190:193], v[54:57]
	v_mfma_f32_16x16x32_bf16 v[50:53], v[152:155], v[190:193], v[50:53]
	v_mfma_f32_16x16x32_bf16 v[42:45], v[144:147], v[198:201], v[42:45]
	v_mfma_f32_16x16x32_bf16 v[34:37], v[152:155], v[198:201], v[34:37]
	v_mfma_f32_16x16x32_bf16 v[26:29], v[144:147], v[236:239], v[26:29]
	v_mfma_f32_16x16x32_bf16 v[18:21], v[152:155], v[236:239], v[18:21]
	v_mfma_f32_16x16x32_bf16 v[62:65], v[148:151], v[186:189], v[62:65]
	v_mfma_f32_16x16x32_bf16 v[58:61], v[156:159], v[186:189], v[58:61]
	v_mfma_f32_16x16x32_bf16 v[54:57], v[148:151], v[194:197], v[54:57]
	v_mfma_f32_16x16x32_bf16 v[50:53], v[156:159], v[194:197], v[50:53]
	v_mfma_f32_16x16x32_bf16 v[42:45], v[148:151], v[202:205], v[42:45]
	v_mfma_f32_16x16x32_bf16 v[34:37], v[156:159], v[202:205], v[34:37]
	v_mfma_f32_16x16x32_bf16 v[26:29], v[148:151], v[240:243], v[26:29]
	v_mfma_f32_16x16x32_bf16 v[18:21], v[156:159], v[240:243], v[18:21]
	v_mfma_f32_16x16x32_bf16 v[46:49], v[160:163], v[182:185], v[46:49]
	v_mfma_f32_16x16x32_bf16 v[38:41], v[174:177], v[182:185], v[38:41]
	v_mfma_f32_16x16x32_bf16 v[30:33], v[160:163], v[190:193], v[30:33]
	v_mfma_f32_16x16x32_bf16 v[22:25], v[174:177], v[190:193], v[22:25]
	v_mfma_f32_16x16x32_bf16 v[14:17], v[160:163], v[198:201], v[14:17]
	v_mfma_f32_16x16x32_bf16 v[10:13], v[174:177], v[198:201], v[10:13]
	v_mfma_f32_16x16x32_bf16 v[6:9], v[160:163], v[236:239], v[6:9]
	v_mfma_f32_16x16x32_bf16 v[2:5], v[174:177], v[236:239], v[2:5]
	v_mfma_f32_16x16x32_bf16 v[46:49], v[164:167], v[186:189], v[46:49]
	v_mfma_f32_16x16x32_bf16 v[38:41], v[178:181], v[186:189], v[38:41]
	v_mfma_f32_16x16x32_bf16 v[30:33], v[164:167], v[194:197], v[30:33]
	v_mfma_f32_16x16x32_bf16 v[22:25], v[178:181], v[194:197], v[22:25]
	v_mfma_f32_16x16x32_bf16 v[14:17], v[164:167], v[202:205], v[14:17]
	v_mfma_f32_16x16x32_bf16 v[10:13], v[178:181], v[202:205], v[10:13]
	v_mfma_f32_16x16x32_bf16 v[6:9], v[164:167], v[240:243], v[6:9]
	v_mfma_f32_16x16x32_bf16 v[2:5], v[178:181], v[240:243], v[2:5]
	s_barrier
	s_setprio 1
	s_add_u32 s18, s18, 0x100
	s_addc_u32 s19, s19, 0
	s_add_u32 s11, s11, 0x100
	s_addc_u32 s15, s15, 0
	s_cmp_ge_u32 vcc_lo, s79
	s_mov_b32 s48, vcc_lo
	s_cbranch_scc0 .LBB0_219
	s_and_b64 vcc, exec, s[8:9]
	s_cbranch_vccz .LBB0_222
	s_barrier

.LBB0_437:
	s_add_u32 s12, s10, 0xfffc0080
	s_addc_u32 s13, s11, -1
	s_add_i32 s36, 0, 0x10000
	s_cmp_eq_u32 s78, 12
	s_cselect_b32 s15, s9, s13
	s_cselect_b32 s14, s45, s12
	s_cselect_b32 s13, s46, s77
	s_cselect_b32 s12, s47, s49
	s_add_i32 s37, 0, 0x14000
	v_add_u32_e32 v156, s36, v145
	v_add_u32_e32 v168, s37, v145
	ds_read_b128 v[140:143], v156
	ds_read_b128 v[148:151], v156 offset:1024
	ds_read_b128 v[152:155], v156 offset:2048
	ds_read_b128 v[156:159], v156 offset:3072
	ds_read_b128 v[160:163], v168
	ds_read_b128 v[164:167], v168 offset:1024
	ds_read_b128 v[174:177], v168 offset:2048
	ds_read_b128 v[178:181], v168 offset:3072
	v_lshl_add_u64 v[168:169], s[10:11], 0, v[136:137]
	s_add_i32 m0, s19, 0xc000
	ds_read_b128 v[182:185], v147
	ds_read_b128 v[186:189], v147 offset:1024
	ds_read_b128 v[190:193], v147 offset:2048
	ds_read_b128 v[194:197], v147 offset:3072
	ds_read_b128 v[198:201], v147 offset:4096
	ds_read_b128 v[202:205], v147 offset:5120
	ds_read_b128 v[236:239], v147 offset:6144
	ds_read_b128 v[240:243], v147 offset:7168
	global_load_lds_dwordx4 v[168:169], off
	v_lshl_add_u64 v[168:169], s[10:11], 0, v[138:139]
	s_add_i32 m0, s19, 0xe000
	s_nop 0
	global_load_lds_dwordx4 v[168:169], off
	s_waitcnt vmcnt(8)
	s_waitcnt lgkmcnt(0)
	s_barrier
	s_setprio 0
	s_waitcnt lgkmcnt(0)
	v_mfma_f32_16x16x32_bf16 v[126:129], v[140:143], v[182:185], v[126:129]
	v_mfma_f32_16x16x32_bf16 v[122:125], v[152:155], v[182:185], v[122:125]
	v_mfma_f32_16x16x32_bf16 v[110:113], v[140:143], v[190:193], v[110:113]
	v_mfma_f32_16x16x32_bf16 v[106:109], v[152:155], v[190:193], v[106:109]
	v_mfma_f32_16x16x32_bf16 v[94:97], v[140:143], v[198:201], v[94:97]
	v_mfma_f32_16x16x32_bf16 v[90:93], v[152:155], v[198:201], v[90:93]
	v_mfma_f32_16x16x32_bf16 v[78:81], v[140:143], v[236:239], v[78:81]
	v_mfma_f32_16x16x32_bf16 v[74:77], v[152:155], v[236:239], v[74:77]
	v_mfma_f32_16x16x32_bf16 v[126:129], v[148:151], v[186:189], v[126:129]
	v_mfma_f32_16x16x32_bf16 v[122:125], v[156:159], v[186:189], v[122:125]
	v_mfma_f32_16x16x32_bf16 v[110:113], v[148:151], v[194:197], v[110:113]
	v_mfma_f32_16x16x32_bf16 v[106:109], v[156:159], v[194:197], v[106:109]
	v_mfma_f32_16x16x32_bf16 v[94:97], v[148:151], v[202:205], v[94:97]
	v_mfma_f32_16x16x32_bf16 v[90:93], v[156:159], v[202:205], v[90:93]
	v_mfma_f32_16x16x32_bf16 v[78:81], v[148:151], v[240:243], v[78:81]
	v_mfma_f32_16x16x32_bf16 v[74:77], v[156:159], v[240:243], v[74:77]
	v_mfma_f32_16x16x32_bf16 v[118:121], v[160:163], v[182:185], v[118:121]
	v_mfma_f32_16x16x32_bf16 v[114:117], v[174:177], v[182:185], v[114:117]
	v_mfma_f32_16x16x32_bf16 v[102:105], v[160:163], v[190:193], v[102:105]
	v_mfma_f32_16x16x32_bf16 v[98:101], v[174:177], v[190:193], v[98:101]
	v_mfma_f32_16x16x32_bf16 v[86:89], v[160:163], v[198:201], v[86:89]
	v_mfma_f32_16x16x32_bf16 v[82:85], v[174:177], v[198:201], v[82:85]
	v_mfma_f32_16x16x32_bf16 v[70:73], v[160:163], v[236:239], v[70:73]
	v_mfma_f32_16x16x32_bf16 v[66:69], v[174:177], v[236:239], v[66:69]
	v_mfma_f32_16x16x32_bf16 v[118:121], v[164:167], v[186:189], v[118:121]
	v_mfma_f32_16x16x32_bf16 v[114:117], v[178:181], v[186:189], v[114:117]
	v_mfma_f32_16x16x32_bf16 v[102:105], v[164:167], v[194:197], v[102:105]
	v_mfma_f32_16x16x32_bf16 v[98:101], v[178:181], v[194:197], v[98:101]
	v_mfma_f32_16x16x32_bf16 v[86:89], v[164:167], v[202:205], v[86:89]
	v_mfma_f32_16x16x32_bf16 v[82:85], v[178:181], v[202:205], v[82:85]
	v_mfma_f32_16x16x32_bf16 v[70:73], v[164:167], v[240:243], v[70:73]
	v_mfma_f32_16x16x32_bf16 v[66:69], v[178:181], v[240:243], v[66:69]
	s_barrier
	s_setprio 1
	s_add_i32 s36, s36, s18
	v_lshl_add_u64 v[168:169], s[12:13], 0, v[0:1]
	s_mov_b32 m0, s36
	ds_read_b128 v[182:185], v147 offset:16384
	ds_read_b128 v[186:189], v147 offset:17408
	ds_read_b128 v[190:193], v147 offset:18432
	ds_read_b128 v[194:197], v147 offset:19456
	ds_read_b128 v[198:201], v147 offset:20480
	ds_read_b128 v[202:205], v147 offset:21504
	ds_read_b128 v[236:239], v147 offset:22528
	ds_read_b128 v[240:243], v147 offset:23552
	global_load_lds_dwordx4 v[168:169], off
	s_add_i32 m0, s36, 0x2000
	s_add_u32 s82, s12, 0x40000
	v_lshl_add_u64 v[206:207], s[12:13], 0, v[130:131]
	s_addc_u32 s83, s13, 0
	s_add_i32 s36, s37, s18
	global_load_lds_dwordx4 v[206:207], off
	v_lshl_add_u64 v[244:245], s[82:83], 0, v[0:1]
	s_mov_b32 m0, s36
	v_lshl_add_u64 v[246:247], s[14:15], 0, v[132:133]
	global_load_lds_dwordx4 v[244:245], off
	v_lshl_add_u64 v[244:245], s[82:83], 0, v[130:131]
	s_add_i32 m0, s36, 0x2000
	s_nop 0
	global_load_lds_dwordx4 v[244:245], off
	v_lshl_add_u64 v[244:245], s[14:15], 0, v[134:135]
	s_mov_b32 m0, s19
	s_nop 0
	global_load_lds_dwordx4 v[244:245], off
	s_mov_b32 m0, s34
	s_nop 0
	global_load_lds_dwordx4 v[246:247], off
	s_waitcnt vmcnt(8)
	s_waitcnt lgkmcnt(0)
	s_barrier
	s_setprio 0
	s_waitcnt lgkmcnt(0)
	v_mfma_f32_16x16x32_bf16 v[62:65], v[140:143], v[182:185], v[62:65]
	v_mfma_f32_16x16x32_bf16 v[58:61], v[152:155], v[182:185], v[58:61]
	v_mfma_f32_16x16x32_bf16 v[46:49], v[140:143], v[190:193], v[46:49]
	v_mfma_f32_16x16x32_bf16 v[42:45], v[152:155], v[190:193], v[42:45]
	v_mfma_f32_16x16x32_bf16 v[30:33], v[140:143], v[198:201], v[30:33]
	v_mfma_f32_16x16x32_bf16 v[26:29], v[152:155], v[198:201], v[26:29]
	v_mfma_f32_16x16x32_bf16 v[14:17], v[140:143], v[236:239], v[14:17]
	v_mfma_f32_16x16x32_bf16 v[10:13], v[152:155], v[236:239], v[10:13]
	v_mfma_f32_16x16x32_bf16 v[62:65], v[148:151], v[186:189], v[62:65]
	v_mfma_f32_16x16x32_bf16 v[58:61], v[156:159], v[186:189], v[58:61]
	v_mfma_f32_16x16x32_bf16 v[46:49], v[148:151], v[194:197], v[46:49]
	v_mfma_f32_16x16x32_bf16 v[42:45], v[156:159], v[194:197], v[42:45]
	v_mfma_f32_16x16x32_bf16 v[30:33], v[148:151], v[202:205], v[30:33]
	v_mfma_f32_16x16x32_bf16 v[26:29], v[156:159], v[202:205], v[26:29]
	v_mfma_f32_16x16x32_bf16 v[14:17], v[148:151], v[240:243], v[14:17]
	v_mfma_f32_16x16x32_bf16 v[10:13], v[156:159], v[240:243], v[10:13]
	v_mfma_f32_16x16x32_bf16 v[54:57], v[160:163], v[182:185], v[54:57]
	v_mfma_f32_16x16x32_bf16 v[50:53], v[174:177], v[182:185], v[50:53]
	v_mfma_f32_16x16x32_bf16 v[38:41], v[160:163], v[190:193], v[38:41]
	v_mfma_f32_16x16x32_bf16 v[34:37], v[174:177], v[190:193], v[34:37]
	v_mfma_f32_16x16x32_bf16 v[22:25], v[160:163], v[198:201], v[22:25]
	v_mfma_f32_16x16x32_bf16 v[18:21], v[174:177], v[198:201], v[18:21]
	v_mfma_f32_16x16x32_bf16 v[6:9], v[160:163], v[236:239], v[6:9]
	v_mfma_f32_16x16x32_bf16 v[2:5], v[174:177], v[236:239], v[2:5]
	v_mfma_f32_16x16x32_bf16 v[54:57], v[164:167], v[186:189], v[54:57]
	v_mfma_f32_16x16x32_bf16 v[50:53], v[178:181], v[186:189], v[50:53]
	v_mfma_f32_16x16x32_bf16 v[38:41], v[164:167], v[194:197], v[38:41]
	v_mfma_f32_16x16x32_bf16 v[34:37], v[178:181], v[194:197], v[34:37]
	v_mfma_f32_16x16x32_bf16 v[22:25], v[164:167], v[202:205], v[22:25]
	v_mfma_f32_16x16x32_bf16 v[18:21], v[178:181], v[202:205], v[18:21]
	v_mfma_f32_16x16x32_bf16 v[6:9], v[164:167], v[240:243], v[6:9]
	v_mfma_f32_16x16x32_bf16 v[2:5], v[178:181], v[240:243], v[2:5]
	s_barrier
	s_setprio 1
	s_add_i32 s36, 0, 0x18000
	s_add_i32 s37, 0, 0x1c000
	v_add_u32_e32 v156, s36, v145
	v_add_u32_e32 v178, s37, v145
	ds_read_b128 v[140:143], v156
	ds_read_b128 v[148:151], v156 offset:1024
	ds_read_b128 v[152:155], v156 offset:2048
	ds_read_b128 v[156:159], v156 offset:3072
	ds_read_b128 v[160:163], v178
	ds_read_b128 v[164:167], v178 offset:1024
	ds_read_b128 v[174:177], v178 offset:2048
	ds_read_b128 v[178:181], v178 offset:3072
	s_add_u32 s14, s14, 0x40000
	s_addc_u32 s15, s15, 0
	s_mov_b32 m0, s54
	v_lshl_add_u64 v[248:249], s[14:15], 0, v[134:135]
	ds_read_b128 v[182:185], v147 offset:32768
	ds_read_b128 v[186:189], v147 offset:33792
	ds_read_b128 v[190:193], v147 offset:34816
	ds_read_b128 v[194:197], v147 offset:35840
	ds_read_b128 v[198:201], v147 offset:36864
	ds_read_b128 v[202:205], v147 offset:37888
	ds_read_b128 v[236:239], v147 offset:38912
	ds_read_b128 v[240:243], v147 offset:39936
	global_load_lds_dwordx4 v[248:249], off
	v_lshl_add_u64 v[248:249], s[14:15], 0, v[132:133]
	s_mov_b32 m0, s55
	s_nop 0
	global_load_lds_dwordx4 v[248:249], off
	s_waitcnt vmcnt(8)
	s_waitcnt lgkmcnt(0)
	s_barrier
	s_setprio 0
	s_waitcnt lgkmcnt(0)
	v_mfma_f32_16x16x32_bf16 v[126:129], v[140:143], v[182:185], v[126:129]
	v_mfma_f32_16x16x32_bf16 v[122:125], v[152:155], v[182:185], v[122:125]
	v_mfma_f32_16x16x32_bf16 v[110:113], v[140:143], v[190:193], v[110:113]
	v_mfma_f32_16x16x32_bf16 v[106:109], v[152:155], v[190:193], v[106:109]
	v_mfma_f32_16x16x32_bf16 v[94:97], v[140:143], v[198:201], v[94:97]
	v_mfma_f32_16x16x32_bf16 v[90:93], v[152:155], v[198:201], v[90:93]
	v_mfma_f32_16x16x32_bf16 v[78:81], v[140:143], v[236:239], v[78:81]
	v_mfma_f32_16x16x32_bf16 v[74:77], v[152:155], v[236:239], v[74:77]
	v_mfma_f32_16x16x32_bf16 v[126:129], v[148:151], v[186:189], v[126:129]
	v_mfma_f32_16x16x32_bf16 v[122:125], v[156:159], v[186:189], v[122:125]
	v_mfma_f32_16x16x32_bf16 v[110:113], v[148:151], v[194:197], v[110:113]
	v_mfma_f32_16x16x32_bf16 v[106:109], v[156:159], v[194:197], v[106:109]
	v_mfma_f32_16x16x32_bf16 v[94:97], v[148:151], v[202:205], v[94:97]
	v_mfma_f32_16x16x32_bf16 v[90:93], v[156:159], v[202:205], v[90:93]
	v_mfma_f32_16x16x32_bf16 v[78:81], v[148:151], v[240:243], v[78:81]
	v_mfma_f32_16x16x32_bf16 v[74:77], v[156:159], v[240:243], v[74:77]
	v_mfma_f32_16x16x32_bf16 v[118:121], v[160:163], v[182:185], v[118:121]
	v_mfma_f32_16x16x32_bf16 v[114:117], v[174:177], v[182:185], v[114:117]
	v_mfma_f32_16x16x32_bf16 v[102:105], v[160:163], v[190:193], v[102:105]
	v_mfma_f32_16x16x32_bf16 v[98:101], v[174:177], v[190:193], v[98:101]
	v_mfma_f32_16x16x32_bf16 v[86:89], v[160:163], v[198:201], v[86:89]
	v_mfma_f32_16x16x32_bf16 v[82:85], v[174:177], v[198:201], v[82:85]
	v_mfma_f32_16x16x32_bf16 v[70:73], v[160:163], v[236:239], v[70:73]
	v_mfma_f32_16x16x32_bf16 v[66:69], v[174:177], v[236:239], v[66:69]
	v_mfma_f32_16x16x32_bf16 v[118:121], v[164:167], v[186:189], v[118:121]
	v_mfma_f32_16x16x32_bf16 v[114:117], v[178:181], v[186:189], v[114:117]
	v_mfma_f32_16x16x32_bf16 v[102:105], v[164:167], v[194:197], v[102:105]
	v_mfma_f32_16x16x32_bf16 v[98:101], v[178:181], v[194:197], v[98:101]
	v_mfma_f32_16x16x32_bf16 v[86:89], v[164:167], v[202:205], v[86:89]
	v_mfma_f32_16x16x32_bf16 v[82:85], v[178:181], v[202:205], v[82:85]
	v_mfma_f32_16x16x32_bf16 v[70:73], v[164:167], v[240:243], v[70:73]
	v_mfma_f32_16x16x32_bf16 v[66:69], v[178:181], v[240:243], v[66:69]
	s_barrier
	s_setprio 1
	s_add_i32 s14, s36, s18
	v_lshl_add_u64 v[168:169], v[168:169], 0, s[4:5]
	s_mov_b32 m0, s14
	ds_read_b128 v[182:185], v147 offset:49152
	ds_read_b128 v[186:189], v147 offset:50176
	ds_read_b128 v[190:193], v147 offset:51200
	ds_read_b128 v[194:197], v147 offset:52224
	ds_read_b128 v[198:201], v147 offset:53248
	ds_read_b128 v[202:205], v147 offset:54272
	ds_read_b128 v[236:239], v147 offset:55296
	ds_read_b128 v[240:243], v147 offset:56320
	global_load_lds_dwordx4 v[168:169], off
	s_add_i32 m0, s14, 0x2000
	s_add_u32 s12, s12, 0x40080
	v_lshl_add_u64 v[168:169], v[206:207], 0, s[4:5]
	s_addc_u32 s13, s13, 0
	s_add_i32 s14, s37, s18
	global_load_lds_dwordx4 v[168:169], off
	v_lshl_add_u64 v[168:169], s[12:13], 0, v[0:1]
	s_mov_b32 m0, s14
	s_nop 0
	global_load_lds_dwordx4 v[168:169], off
	v_lshl_add_u64 v[168:169], s[12:13], 0, v[130:131]
	s_add_i32 m0, s14, 0x2000
	s_nop 0
	global_load_lds_dwordx4 v[168:169], off
	v_lshl_add_u64 v[168:169], v[244:245], 0, s[4:5]
	s_mov_b32 m0, s70
	s_nop 0
	global_load_lds_dwordx4 v[168:169], off
	v_lshl_add_u64 v[168:169], v[246:247], 0, s[4:5]
	s_mov_b32 m0, s71
	s_nop 0
	global_load_lds_dwordx4 v[168:169], off
	s_waitcnt vmcnt(8)
	s_waitcnt lgkmcnt(0)
	s_barrier
	s_setprio 0
	s_waitcnt lgkmcnt(0)
	v_mfma_f32_16x16x32_bf16 v[62:65], v[140:143], v[182:185], v[62:65]
	v_mfma_f32_16x16x32_bf16 v[58:61], v[152:155], v[182:185], v[58:61]
	v_mfma_f32_16x16x32_bf16 v[46:49], v[140:143], v[190:193], v[46:49]
	v_mfma_f32_16x16x32_bf16 v[42:45], v[152:155], v[190:193], v[42:45]
	v_mfma_f32_16x16x32_bf16 v[30:33], v[140:143], v[198:201], v[30:33]
	v_mfma_f32_16x16x32_bf16 v[26:29], v[152:155], v[198:201], v[26:29]
	v_mfma_f32_16x16x32_bf16 v[14:17], v[140:143], v[236:239], v[14:17]
	v_mfma_f32_16x16x32_bf16 v[10:13], v[152:155], v[236:239], v[10:13]
	v_mfma_f32_16x16x32_bf16 v[62:65], v[148:151], v[186:189], v[62:65]
	v_mfma_f32_16x16x32_bf16 v[58:61], v[156:159], v[186:189], v[58:61]
	v_mfma_f32_16x16x32_bf16 v[46:49], v[148:151], v[194:197], v[46:49]
	v_mfma_f32_16x16x32_bf16 v[42:45], v[156:159], v[194:197], v[42:45]
	v_mfma_f32_16x16x32_bf16 v[30:33], v[148:151], v[202:205], v[30:33]
	v_mfma_f32_16x16x32_bf16 v[26:29], v[156:159], v[202:205], v[26:29]
	v_mfma_f32_16x16x32_bf16 v[14:17], v[148:151], v[240:243], v[14:17]
	v_mfma_f32_16x16x32_bf16 v[10:13], v[156:159], v[240:243], v[10:13]
	v_mfma_f32_16x16x32_bf16 v[54:57], v[160:163], v[182:185], v[54:57]
	v_mfma_f32_16x16x32_bf16 v[50:53], v[174:177], v[182:185], v[50:53]
	v_mfma_f32_16x16x32_bf16 v[38:41], v[160:163], v[190:193], v[38:41]
	v_mfma_f32_16x16x32_bf16 v[34:37], v[174:177], v[190:193], v[34:37]
	v_mfma_f32_16x16x32_bf16 v[22:25], v[160:163], v[198:201], v[22:25]
	v_mfma_f32_16x16x32_bf16 v[18:21], v[174:177], v[198:201], v[18:21]
	v_mfma_f32_16x16x32_bf16 v[6:9], v[160:163], v[236:239], v[6:9]
	v_mfma_f32_16x16x32_bf16 v[2:5], v[174:177], v[236:239], v[2:5]
	v_mfma_f32_16x16x32_bf16 v[54:57], v[164:167], v[186:189], v[54:57]
	v_mfma_f32_16x16x32_bf16 v[50:53], v[178:181], v[186:189], v[50:53]
	v_mfma_f32_16x16x32_bf16 v[38:41], v[164:167], v[194:197], v[38:41]
	v_mfma_f32_16x16x32_bf16 v[34:37], v[178:181], v[194:197], v[34:37]
	v_mfma_f32_16x16x32_bf16 v[22:25], v[164:167], v[202:205], v[22:25]
	v_mfma_f32_16x16x32_bf16 v[18:21], v[178:181], v[202:205], v[18:21]
	v_mfma_f32_16x16x32_bf16 v[6:9], v[164:167], v[240:243], v[6:9]
	v_mfma_f32_16x16x32_bf16 v[2:5], v[178:181], v[240:243], v[2:5]
	s_barrier
	s_setprio 1
	s_add_i32 s78, s78, 2
	s_add_u32 s10, s10, 0x100
	s_addc_u32 s11, s11, 0
	s_add_u32 s49, s49, 0x100
	s_addc_u32 s77, s77, 0
	s_cmp_gt_u32 s78, 13
	s_cbranch_scc0 .LBB0_437
	s_and_b64 vcc, exec, s[6:7]
	s_cbranch_vccz .LBB0_440
	s_barrier

.LBB0_493:
	s_add_u32 s16, s14, 0xfffc0080
	s_addc_u32 s17, s15, -1
	s_add_i32 s36, 0, 0x10000
	s_cmp_eq_u32 s46, 12
	s_cselect_b32 s19, s11, s17
	s_cselect_b32 s18, s13, s16
	s_cselect_b32 s17, s40, s45
	s_cselect_b32 s16, s41, s44
	s_add_i32 s37, 0, 0x14000
	v_add_u32_e32 v156, s36, v145
	v_add_u32_e32 v168, s37, v145
	ds_read_b128 v[140:143], v156
	ds_read_b128 v[148:151], v156 offset:1024
	ds_read_b128 v[152:155], v156 offset:2048
	ds_read_b128 v[156:159], v156 offset:3072
	ds_read_b128 v[160:163], v168
	ds_read_b128 v[164:167], v168 offset:1024
	ds_read_b128 v[174:177], v168 offset:2048
	ds_read_b128 v[178:181], v168 offset:3072
	v_lshl_add_u64 v[168:169], s[14:15], 0, v[136:137]
	s_add_i32 m0, s74, 0xc000
	ds_read_b128 v[182:185], v147
	ds_read_b128 v[186:189], v147 offset:1024
	ds_read_b128 v[190:193], v147 offset:2048
	ds_read_b128 v[194:197], v147 offset:3072
	ds_read_b128 v[198:201], v147 offset:4096
	ds_read_b128 v[202:205], v147 offset:5120
	ds_read_b128 v[236:239], v147 offset:6144
	ds_read_b128 v[240:243], v147 offset:7168
	global_load_lds_dwordx4 v[168:169], off
	v_lshl_add_u64 v[168:169], s[14:15], 0, v[138:139]
	s_add_i32 m0, s74, 0xe000
	s_nop 0
	global_load_lds_dwordx4 v[168:169], off
	s_waitcnt vmcnt(8)
	s_waitcnt lgkmcnt(0)
	s_barrier
	s_setprio 0
	s_waitcnt lgkmcnt(0)
	v_mfma_f32_16x16x32_bf16 v[126:129], v[140:143], v[182:185], v[126:129]
	v_mfma_f32_16x16x32_bf16 v[122:125], v[152:155], v[182:185], v[122:125]
	v_mfma_f32_16x16x32_bf16 v[110:113], v[140:143], v[190:193], v[110:113]
	v_mfma_f32_16x16x32_bf16 v[106:109], v[152:155], v[190:193], v[106:109]
	v_mfma_f32_16x16x32_bf16 v[94:97], v[140:143], v[198:201], v[94:97]
	v_mfma_f32_16x16x32_bf16 v[90:93], v[152:155], v[198:201], v[90:93]
	v_mfma_f32_16x16x32_bf16 v[78:81], v[140:143], v[236:239], v[78:81]
	v_mfma_f32_16x16x32_bf16 v[74:77], v[152:155], v[236:239], v[74:77]
	v_mfma_f32_16x16x32_bf16 v[126:129], v[148:151], v[186:189], v[126:129]
	v_mfma_f32_16x16x32_bf16 v[122:125], v[156:159], v[186:189], v[122:125]
	v_mfma_f32_16x16x32_bf16 v[110:113], v[148:151], v[194:197], v[110:113]
	v_mfma_f32_16x16x32_bf16 v[106:109], v[156:159], v[194:197], v[106:109]
	v_mfma_f32_16x16x32_bf16 v[94:97], v[148:151], v[202:205], v[94:97]
	v_mfma_f32_16x16x32_bf16 v[90:93], v[156:159], v[202:205], v[90:93]
	v_mfma_f32_16x16x32_bf16 v[78:81], v[148:151], v[240:243], v[78:81]
	v_mfma_f32_16x16x32_bf16 v[74:77], v[156:159], v[240:243], v[74:77]
	v_mfma_f32_16x16x32_bf16 v[118:121], v[160:163], v[182:185], v[118:121]
	v_mfma_f32_16x16x32_bf16 v[114:117], v[174:177], v[182:185], v[114:117]
	v_mfma_f32_16x16x32_bf16 v[102:105], v[160:163], v[190:193], v[102:105]
	v_mfma_f32_16x16x32_bf16 v[98:101], v[174:177], v[190:193], v[98:101]
	v_mfma_f32_16x16x32_bf16 v[86:89], v[160:163], v[198:201], v[86:89]
	v_mfma_f32_16x16x32_bf16 v[82:85], v[174:177], v[198:201], v[82:85]
	v_mfma_f32_16x16x32_bf16 v[70:73], v[160:163], v[236:239], v[70:73]
	v_mfma_f32_16x16x32_bf16 v[66:69], v[174:177], v[236:239], v[66:69]
	v_mfma_f32_16x16x32_bf16 v[118:121], v[164:167], v[186:189], v[118:121]
	v_mfma_f32_16x16x32_bf16 v[114:117], v[178:181], v[186:189], v[114:117]
	v_mfma_f32_16x16x32_bf16 v[102:105], v[164:167], v[194:197], v[102:105]
	v_mfma_f32_16x16x32_bf16 v[98:101], v[178:181], v[194:197], v[98:101]
	v_mfma_f32_16x16x32_bf16 v[86:89], v[164:167], v[202:205], v[86:89]
	v_mfma_f32_16x16x32_bf16 v[82:85], v[178:181], v[202:205], v[82:85]
	v_mfma_f32_16x16x32_bf16 v[70:73], v[164:167], v[240:243], v[70:73]
	v_mfma_f32_16x16x32_bf16 v[66:69], v[178:181], v[240:243], v[66:69]
	s_barrier
	s_setprio 1
	s_add_i32 s36, s36, s71
	v_lshl_add_u64 v[168:169], s[16:17], 0, v[0:1]
	s_mov_b32 m0, s36
	ds_read_b128 v[182:185], v147 offset:16384
	ds_read_b128 v[186:189], v147 offset:17408
	ds_read_b128 v[190:193], v147 offset:18432
	ds_read_b128 v[194:197], v147 offset:19456
	ds_read_b128 v[198:201], v147 offset:20480
	ds_read_b128 v[202:205], v147 offset:21504
	ds_read_b128 v[236:239], v147 offset:22528
	ds_read_b128 v[240:243], v147 offset:23552
	global_load_lds_dwordx4 v[168:169], off
	s_add_i32 m0, s36, 0x2000
	s_add_u32 s88, s16, 0x40000
	v_lshl_add_u64 v[206:207], s[16:17], 0, v[134:135]
	s_addc_u32 s89, s17, 0
	s_add_i32 s36, s37, s71
	global_load_lds_dwordx4 v[206:207], off
	v_lshl_add_u64 v[244:245], s[88:89], 0, v[0:1]
	s_mov_b32 m0, s36
	v_lshl_add_u64 v[246:247], s[18:19], 0, v[132:133]
	global_load_lds_dwordx4 v[244:245], off
	v_lshl_add_u64 v[244:245], s[88:89], 0, v[134:135]
	s_add_i32 m0, s36, 0x2000
	s_nop 0
	global_load_lds_dwordx4 v[244:245], off
	v_lshl_add_u64 v[244:245], s[18:19], 0, v[130:131]
	s_mov_b32 m0, s74
	s_nop 0
	global_load_lds_dwordx4 v[244:245], off
	s_mov_b32 m0, s75
	s_nop 0
	global_load_lds_dwordx4 v[246:247], off
	s_waitcnt vmcnt(8)
	s_waitcnt lgkmcnt(0)
	s_barrier
	s_setprio 0
	s_waitcnt lgkmcnt(0)
	v_mfma_f32_16x16x32_bf16 v[62:65], v[140:143], v[182:185], v[62:65]
	v_mfma_f32_16x16x32_bf16 v[58:61], v[152:155], v[182:185], v[58:61]
	v_mfma_f32_16x16x32_bf16 v[46:49], v[140:143], v[190:193], v[46:49]
	v_mfma_f32_16x16x32_bf16 v[42:45], v[152:155], v[190:193], v[42:45]
	v_mfma_f32_16x16x32_bf16 v[30:33], v[140:143], v[198:201], v[30:33]
	v_mfma_f32_16x16x32_bf16 v[26:29], v[152:155], v[198:201], v[26:29]
	v_mfma_f32_16x16x32_bf16 v[14:17], v[140:143], v[236:239], v[14:17]
	v_mfma_f32_16x16x32_bf16 v[10:13], v[152:155], v[236:239], v[10:13]
	v_mfma_f32_16x16x32_bf16 v[62:65], v[148:151], v[186:189], v[62:65]
	v_mfma_f32_16x16x32_bf16 v[58:61], v[156:159], v[186:189], v[58:61]
	v_mfma_f32_16x16x32_bf16 v[46:49], v[148:151], v[194:197], v[46:49]
	v_mfma_f32_16x16x32_bf16 v[42:45], v[156:159], v[194:197], v[42:45]
	v_mfma_f32_16x16x32_bf16 v[30:33], v[148:151], v[202:205], v[30:33]
	v_mfma_f32_16x16x32_bf16 v[26:29], v[156:159], v[202:205], v[26:29]
	v_mfma_f32_16x16x32_bf16 v[14:17], v[148:151], v[240:243], v[14:17]
	v_mfma_f32_16x16x32_bf16 v[10:13], v[156:159], v[240:243], v[10:13]
	v_mfma_f32_16x16x32_bf16 v[54:57], v[160:163], v[182:185], v[54:57]
	v_mfma_f32_16x16x32_bf16 v[50:53], v[174:177], v[182:185], v[50:53]
	v_mfma_f32_16x16x32_bf16 v[38:41], v[160:163], v[190:193], v[38:41]
	v_mfma_f32_16x16x32_bf16 v[34:37], v[174:177], v[190:193], v[34:37]
	v_mfma_f32_16x16x32_bf16 v[22:25], v[160:163], v[198:201], v[22:25]
	v_mfma_f32_16x16x32_bf16 v[18:21], v[174:177], v[198:201], v[18:21]
	v_mfma_f32_16x16x32_bf16 v[6:9], v[160:163], v[236:239], v[6:9]
	v_mfma_f32_16x16x32_bf16 v[2:5], v[174:177], v[236:239], v[2:5]
	v_mfma_f32_16x16x32_bf16 v[54:57], v[164:167], v[186:189], v[54:57]
	v_mfma_f32_16x16x32_bf16 v[50:53], v[178:181], v[186:189], v[50:53]
	v_mfma_f32_16x16x32_bf16 v[38:41], v[164:167], v[194:197], v[38:41]
	v_mfma_f32_16x16x32_bf16 v[34:37], v[178:181], v[194:197], v[34:37]
	v_mfma_f32_16x16x32_bf16 v[22:25], v[164:167], v[202:205], v[22:25]
	v_mfma_f32_16x16x32_bf16 v[18:21], v[178:181], v[202:205], v[18:21]
	v_mfma_f32_16x16x32_bf16 v[6:9], v[164:167], v[240:243], v[6:9]
	v_mfma_f32_16x16x32_bf16 v[2:5], v[178:181], v[240:243], v[2:5]
	s_barrier
	s_setprio 1
	s_add_i32 s36, 0, 0x18000
	s_add_i32 s37, 0, 0x1c000
	v_add_u32_e32 v156, s36, v145
	v_add_u32_e32 v178, s37, v145
	ds_read_b128 v[140:143], v156
	ds_read_b128 v[148:151], v156 offset:1024
	ds_read_b128 v[152:155], v156 offset:2048
	ds_read_b128 v[156:159], v156 offset:3072
	ds_read_b128 v[160:163], v178
	ds_read_b128 v[164:167], v178 offset:1024
	ds_read_b128 v[174:177], v178 offset:2048
	ds_read_b128 v[178:181], v178 offset:3072
	s_add_u32 s18, s18, 0x40000
	s_addc_u32 s19, s19, 0
	s_mov_b32 m0, s77
	v_lshl_add_u64 v[248:249], s[18:19], 0, v[130:131]
	ds_read_b128 v[182:185], v147 offset:32768
	ds_read_b128 v[186:189], v147 offset:33792
	ds_read_b128 v[190:193], v147 offset:34816
	ds_read_b128 v[194:197], v147 offset:35840
	ds_read_b128 v[198:201], v147 offset:36864
	ds_read_b128 v[202:205], v147 offset:37888
	ds_read_b128 v[236:239], v147 offset:38912
	ds_read_b128 v[240:243], v147 offset:39936
	global_load_lds_dwordx4 v[248:249], off
	v_lshl_add_u64 v[248:249], s[18:19], 0, v[132:133]
	s_mov_b32 m0, s78
	s_nop 0
	global_load_lds_dwordx4 v[248:249], off
	s_waitcnt vmcnt(8)
	s_waitcnt lgkmcnt(0)
	s_barrier
	s_setprio 0
	s_waitcnt lgkmcnt(0)
	v_mfma_f32_16x16x32_bf16 v[126:129], v[140:143], v[182:185], v[126:129]
	v_mfma_f32_16x16x32_bf16 v[122:125], v[152:155], v[182:185], v[122:125]
	v_mfma_f32_16x16x32_bf16 v[110:113], v[140:143], v[190:193], v[110:113]
	v_mfma_f32_16x16x32_bf16 v[106:109], v[152:155], v[190:193], v[106:109]
	v_mfma_f32_16x16x32_bf16 v[94:97], v[140:143], v[198:201], v[94:97]
	v_mfma_f32_16x16x32_bf16 v[90:93], v[152:155], v[198:201], v[90:93]
	v_mfma_f32_16x16x32_bf16 v[78:81], v[140:143], v[236:239], v[78:81]
	v_mfma_f32_16x16x32_bf16 v[74:77], v[152:155], v[236:239], v[74:77]
	v_mfma_f32_16x16x32_bf16 v[126:129], v[148:151], v[186:189], v[126:129]
	v_mfma_f32_16x16x32_bf16 v[122:125], v[156:159], v[186:189], v[122:125]
	v_mfma_f32_16x16x32_bf16 v[110:113], v[148:151], v[194:197], v[110:113]
	v_mfma_f32_16x16x32_bf16 v[106:109], v[156:159], v[194:197], v[106:109]
	v_mfma_f32_16x16x32_bf16 v[94:97], v[148:151], v[202:205], v[94:97]
	v_mfma_f32_16x16x32_bf16 v[90:93], v[156:159], v[202:205], v[90:93]
	v_mfma_f32_16x16x32_bf16 v[78:81], v[148:151], v[240:243], v[78:81]
	v_mfma_f32_16x16x32_bf16 v[74:77], v[156:159], v[240:243], v[74:77]
	v_mfma_f32_16x16x32_bf16 v[118:121], v[160:163], v[182:185], v[118:121]
	v_mfma_f32_16x16x32_bf16 v[114:117], v[174:177], v[182:185], v[114:117]
	v_mfma_f32_16x16x32_bf16 v[102:105], v[160:163], v[190:193], v[102:105]
	v_mfma_f32_16x16x32_bf16 v[98:101], v[174:177], v[190:193], v[98:101]
	v_mfma_f32_16x16x32_bf16 v[86:89], v[160:163], v[198:201], v[86:89]
	v_mfma_f32_16x16x32_bf16 v[82:85], v[174:177], v[198:201], v[82:85]
	v_mfma_f32_16x16x32_bf16 v[70:73], v[160:163], v[236:239], v[70:73]
	v_mfma_f32_16x16x32_bf16 v[66:69], v[174:177], v[236:239], v[66:69]
	v_mfma_f32_16x16x32_bf16 v[118:121], v[164:167], v[186:189], v[118:121]
	v_mfma_f32_16x16x32_bf16 v[114:117], v[178:181], v[186:189], v[114:117]
	v_mfma_f32_16x16x32_bf16 v[102:105], v[164:167], v[194:197], v[102:105]
	v_mfma_f32_16x16x32_bf16 v[98:101], v[178:181], v[194:197], v[98:101]
	v_mfma_f32_16x16x32_bf16 v[86:89], v[164:167], v[202:205], v[86:89]
	v_mfma_f32_16x16x32_bf16 v[82:85], v[178:181], v[202:205], v[82:85]
	v_mfma_f32_16x16x32_bf16 v[70:73], v[164:167], v[240:243], v[70:73]
	v_mfma_f32_16x16x32_bf16 v[66:69], v[178:181], v[240:243], v[66:69]
	s_barrier
	s_setprio 1
	s_add_i32 s18, s36, s71
	v_lshl_add_u64 v[168:169], v[168:169], 0, s[4:5]
	s_mov_b32 m0, s18
	ds_read_b128 v[182:185], v147 offset:49152
	ds_read_b128 v[186:189], v147 offset:50176
	ds_read_b128 v[190:193], v147 offset:51200
	ds_read_b128 v[194:197], v147 offset:52224
	ds_read_b128 v[198:201], v147 offset:53248
	ds_read_b128 v[202:205], v147 offset:54272
	ds_read_b128 v[236:239], v147 offset:55296
	ds_read_b128 v[240:243], v147 offset:56320
	global_load_lds_dwordx4 v[168:169], off
	s_add_i32 m0, s18, 0x2000
	s_add_u32 s16, s16, 0x40080
	v_lshl_add_u64 v[168:169], v[206:207], 0, s[4:5]
	s_addc_u32 s17, s17, 0
	s_add_i32 s18, s37, s71
	global_load_lds_dwordx4 v[168:169], off
	v_lshl_add_u64 v[168:169], s[16:17], 0, v[0:1]
	s_mov_b32 m0, s18
	s_nop 0
	global_load_lds_dwordx4 v[168:169], off
	v_lshl_add_u64 v[168:169], s[16:17], 0, v[134:135]
	s_add_i32 m0, s18, 0x2000
	s_nop 0
	global_load_lds_dwordx4 v[168:169], off
	v_lshl_add_u64 v[168:169], v[244:245], 0, s[4:5]
	s_mov_b32 m0, s79
	s_nop 0
	global_load_lds_dwordx4 v[168:169], off
	v_lshl_add_u64 v[168:169], v[246:247], 0, s[4:5]
	s_mov_b32 m0, s82
	s_nop 0
	global_load_lds_dwordx4 v[168:169], off
	s_waitcnt vmcnt(8)
	s_waitcnt lgkmcnt(0)
	s_barrier
	s_setprio 0
	s_waitcnt lgkmcnt(0)
	v_mfma_f32_16x16x32_bf16 v[62:65], v[140:143], v[182:185], v[62:65]
	v_mfma_f32_16x16x32_bf16 v[58:61], v[152:155], v[182:185], v[58:61]
	v_mfma_f32_16x16x32_bf16 v[46:49], v[140:143], v[190:193], v[46:49]
	v_mfma_f32_16x16x32_bf16 v[42:45], v[152:155], v[190:193], v[42:45]
	v_mfma_f32_16x16x32_bf16 v[30:33], v[140:143], v[198:201], v[30:33]
	v_mfma_f32_16x16x32_bf16 v[26:29], v[152:155], v[198:201], v[26:29]
	v_mfma_f32_16x16x32_bf16 v[14:17], v[140:143], v[236:239], v[14:17]
	v_mfma_f32_16x16x32_bf16 v[10:13], v[152:155], v[236:239], v[10:13]
	v_mfma_f32_16x16x32_bf16 v[62:65], v[148:151], v[186:189], v[62:65]
	v_mfma_f32_16x16x32_bf16 v[58:61], v[156:159], v[186:189], v[58:61]
	v_mfma_f32_16x16x32_bf16 v[46:49], v[148:151], v[194:197], v[46:49]
	v_mfma_f32_16x16x32_bf16 v[42:45], v[156:159], v[194:197], v[42:45]
	v_mfma_f32_16x16x32_bf16 v[30:33], v[148:151], v[202:205], v[30:33]
	v_mfma_f32_16x16x32_bf16 v[26:29], v[156:159], v[202:205], v[26:29]
	v_mfma_f32_16x16x32_bf16 v[14:17], v[148:151], v[240:243], v[14:17]
	v_mfma_f32_16x16x32_bf16 v[10:13], v[156:159], v[240:243], v[10:13]
	v_mfma_f32_16x16x32_bf16 v[54:57], v[160:163], v[182:185], v[54:57]
	v_mfma_f32_16x16x32_bf16 v[50:53], v[174:177], v[182:185], v[50:53]
	v_mfma_f32_16x16x32_bf16 v[38:41], v[160:163], v[190:193], v[38:41]
	v_mfma_f32_16x16x32_bf16 v[34:37], v[174:177], v[190:193], v[34:37]
	v_mfma_f32_16x16x32_bf16 v[22:25], v[160:163], v[198:201], v[22:25]
	v_mfma_f32_16x16x32_bf16 v[18:21], v[174:177], v[198:201], v[18:21]
	v_mfma_f32_16x16x32_bf16 v[6:9], v[160:163], v[236:239], v[6:9]
	v_mfma_f32_16x16x32_bf16 v[2:5], v[174:177], v[236:239], v[2:5]
	v_mfma_f32_16x16x32_bf16 v[54:57], v[164:167], v[186:189], v[54:57]
	v_mfma_f32_16x16x32_bf16 v[50:53], v[178:181], v[186:189], v[50:53]
	v_mfma_f32_16x16x32_bf16 v[38:41], v[164:167], v[194:197], v[38:41]
	v_mfma_f32_16x16x32_bf16 v[34:37], v[178:181], v[194:197], v[34:37]
	v_mfma_f32_16x16x32_bf16 v[22:25], v[164:167], v[202:205], v[22:25]
	v_mfma_f32_16x16x32_bf16 v[18:21], v[178:181], v[202:205], v[18:21]
	v_mfma_f32_16x16x32_bf16 v[6:9], v[164:167], v[240:243], v[6:9]
	v_mfma_f32_16x16x32_bf16 v[2:5], v[178:181], v[240:243], v[2:5]
	s_barrier
	s_setprio 1
	s_add_i32 s46, s46, 2
	s_add_u32 s14, s14, 0x100
	s_addc_u32 s15, s15, 0
	s_add_u32 s44, s44, 0x100
	s_addc_u32 s45, s45, 0
	s_cmp_gt_u32 s46, 13
	s_cbranch_scc0 .LBB0_493
	s_and_b64 vcc, exec, s[8:9]
	s_cbranch_vccz .LBB0_496
	s_barrier
